# P2 epilogues de-serialised: hoist 8 SSQ loads (EpiQB+EpiKV) and 16 cos/sin loads (EpiQB) to epilogue top, one round trip instead of 8-16
# baseline (speedup 1.0000x reference)
.LBB0_335:
	v_lshl_add_u32 v148, s6, 8, v160
	v_ashrrev_i32_e32 v149, 31, v148
	v_lshl_add_u64 v[150:151], v[148:149], 2, s[44:45]
	global_load_dword v202, v[150:151], off
	global_load_dword v203, v[150:151], off offset:64
	global_load_dword v230, v[150:151], off offset:128
	global_load_dword v231, v[150:151], off offset:192
	global_load_dword v252, v[150:151], off offset:512
	global_load_dword v253, v[150:151], off offset:576
	global_load_dword v255, v[150:151], off offset:640
	global_load_dword v167, v[150:151], off offset:704
	v_lshlrev_b64 v[152:153], 5, v[148:149]
	s_lshl_b32 s0, s0, 8
	s_or_b32 s0, s0, s85
	s_mul_hi_i32 s1, s0, 0x2aaaaaab
	s_lshr_b32 s6, s1, 31
	s_lshr_b32 s1, s1, 5
	s_add_i32 s1, s1, s6
	s_mulk_i32 s1, 0xc0
	s_sub_i32 s51, s0, s1
	s_and_b32 s100, s51, 0xc0
	s_cmp_eq_u32 s100, 64
	s_cbranch_scc1 .Lp2a_norope0
	s_and_b32 s100, s51, 32
	s_lshl_b32 s100, s100, 1
	v_lshlrev_b32_e32 v184, 7, v148
	v_lshl_add_u32 v184, v162, 2, v184
	v_add_u32_e32 v184, s100, v184
	v_add_u32_e32 v185, 0x1000, v184
	v_add_u32_e32 v186, 0x4000, v184
	v_add_u32_e32 v187, 0x5000, v184
	global_load_dwordx4 v[190:193], v184, s[12:13]
	global_load_dwordx4 v[194:197], v184, s[14:15]
	global_load_dwordx4 v[198:201], v184, s[12:13] offset:2048
	global_load_dwordx4 v[206:209], v184, s[14:15] offset:2048
	global_load_dwordx4 v[210:213], v185, s[12:13]
	global_load_dwordx4 v[214:217], v185, s[14:15]
	global_load_dwordx4 v[218:221], v185, s[12:13] offset:2048
	global_load_dwordx4 v[222:225], v185, s[14:15] offset:2048
	global_load_dwordx4 v[226:229], v186, s[12:13]
	global_load_dwordx4 v[232:235], v186, s[14:15]
	global_load_dwordx4 v[236:239], v186, s[12:13] offset:2048
	global_load_dwordx4 v[240:243], v186, s[14:15] offset:2048
	global_load_dwordx4 v[244:247], v187, s[12:13]
	global_load_dwordx4 v[248:251], v187, s[14:15]
.Lp2a_norope0:
	v_lshlrev_b64 v[168:169], 2, v[152:153]
	s_cmpk_gt_i32 s51, 0x7f
	v_lshl_add_u64 v[152:153], s[12:13], 0, v[168:169]
	s_cselect_b64 s[8:9], -1, 0
	s_cmpk_lt_i32 s51, 0x80
	s_waitcnt vmcnt(0)
	v_mov_b32_e32 v136, v202
	v_fmamk_f32 v136, v136, 0x3b000000, v166
	v_mul_f32_e32 v149, 0x4b800000, v136
	v_cmp_gt_f32_e32 vcc, s94, v136
	s_nop 1
	v_cndmask_b32_e32 v136, v136, v149, vcc
	v_rsq_f32_e32 v136, v136
	s_nop 0
	v_mul_f32_e32 v149, 0x45800000, v136
	v_cndmask_b32_e32 v136, v136, v149, vcc
	v_mul_f32_e32 v154, 0x3dd53b94, v136
	v_pk_mul_f32 v[158:159], v[126:127], v[154:155] op_sel_hi:[1,0]
	v_pk_mul_f32 v[126:127], v[124:125], v[154:155] op_sel_hi:[1,0]
	v_pk_mul_f32 v[156:157], v[122:123], v[154:155] op_sel_hi:[1,0]
	v_pk_mul_f32 v[124:125], v[120:121], v[154:155] op_sel_hi:[1,0]
	v_lshl_add_u64 v[122:123], s[14:15], 0, v[168:169]
	s_cbranch_scc1 .LBB0_337
	s_add_i32 s1, s51, 0xffffff80
	s_lshr_b32 s1, s1, 1
	v_or_b32_e32 v136, s1, v162
	v_lshlrev_b64 v[120:121], 2, v[136:137]
	v_lshl_add_u64 v[168:169], v[152:153], 0, v[120:121]
	v_lshl_add_u64 v[120:121], v[122:123], 0, v[120:121]
	v_mov_b64_e32 v[168:169], v[190:191]
	v_mov_b64_e32 v[170:171], v[192:193]
	v_mov_b64_e32 v[172:173], v[194:195]
	v_mov_b64_e32 v[174:175], v[196:197]
	v_pk_mul_f32 v[120:121], v[126:127], v[168:169]
	v_pk_mul_f32 v[176:177], v[126:127], v[172:173] op_sel:[1,0] op_sel_hi:[0,0]
	v_pk_mul_f32 v[182:183], v[124:125], v[174:175] op_sel:[1,0] op_sel_hi:[0,0]
	v_mov_b32_e32 v172, v169
	v_mul_f32_e32 v136, v159, v173
	v_mul_f32_e32 v178, v159, v169
	v_pk_mul_f32 v[180:181], v[124:125], v[170:171]
	v_mov_b32_e32 v174, v171
	v_mul_f32_e32 v184, v157, v175
	v_mul_f32_e32 v186, v157, v171
	v_pk_fma_f32 v[126:127], v[126:127], v[168:169], v[176:177] op_sel_hi:[1,0,1]
	v_mov_b32_e32 v168, v173
	v_pk_fma_f32 v[124:125], v[124:125], v[170:171], v[182:183] op_sel_hi:[1,0,1]
	v_mov_b32_e32 v170, v175
	v_pk_fma_f32 v[188:189], v[158:159], v[172:173], v[136:137] op_sel_hi:[1,1,0] neg_lo:[0,0,1] neg_hi:[0,0,1]
	v_pk_fma_f32 v[172:173], v[156:157], v[174:175], v[184:185] op_sel_hi:[1,1,0] neg_lo:[0,0,1] neg_hi:[0,0,1]
	v_pk_fma_f32 v[168:169], v[158:159], v[168:169], v[178:179] op_sel_hi:[1,1,0]
	v_pk_fma_f32 v[170:171], v[156:157], v[170:171], v[186:187] op_sel_hi:[1,1,0]
	v_sub_f32_e32 v124, v180, v182
	v_sub_f32_e32 v126, v120, v176
	v_mov_b32_e32 v156, v172
	v_mov_b32_e32 v158, v188
	v_mov_b32_e32 v157, v170
	v_mov_b32_e32 v159, v168
.LBB0_337:
	v_cvt_pk_bf16_f32 v168, v126, v127
	v_cvt_pk_bf16_f32 v169, v158, v159
	v_cvt_pk_bf16_f32 v170, v124, v125
	v_mov_b64_e32 v[124:125], s[40:41]
	v_mad_i64_i32 v[124:125], s[6:7], v148, s95, v[124:125]
	s_or_b32 s1, s0, 0x80
	s_mul_hi_i32 s6, s1, 0x2aaaaaab
	s_lshr_b32 s7, s6, 31
	s_lshr_b32 s6, s6, 5
	v_or_b32_e32 v120, s0, v138
	s_add_i32 s6, s6, s7
	v_ashrrev_i32_e32 v121, 31, v120
	s_mulk_i32 s6, 0xc0
	v_lshl_add_u64 v[126:127], v[120:121], 1, v[124:125]
	s_sub_i32 s53, s1, s6
	v_mov_b32_e32 v155, v154
	v_cvt_pk_bf16_f32 v171, v156, v157
	global_store_dwordx4 v[126:127], v[168:171], off
	v_mov_b32_e32 v126, v154
	v_mov_b32_e32 v127, v154
	s_cmpk_gt_i32 s53, 0x7f
	v_pk_mul_f32 v[118:119], v[118:119], v[126:127]
	v_pk_mul_f32 v[116:117], v[116:117], v[154:155]
	v_pk_mul_f32 v[114:115], v[114:115], v[126:127]
	s_cselect_b64 s[74:75], -1, 0
	s_cmpk_lt_i32 s53, 0x80
	v_pk_mul_f32 v[112:113], v[112:113], v[154:155]
	s_cbranch_scc1 .LBB0_339
	s_add_i32 s1, s53, 0xffffff80
	s_lshr_b32 s1, s1, 1
	v_or_b32_e32 v136, s1, v162
	v_lshlrev_b64 v[126:127], 2, v[136:137]
	v_lshl_add_u64 v[152:153], v[152:153], 0, v[126:127]
	v_lshl_add_u64 v[122:123], v[122:123], 0, v[126:127]
	v_mov_b64_e32 v[152:153], v[190:191]
	v_mov_b64_e32 v[154:155], v[192:193]
	v_mov_b64_e32 v[156:157], v[194:195]
	v_mov_b64_e32 v[158:159], v[196:197]
	v_pk_mul_f32 v[122:123], v[116:117], v[152:153]
	v_pk_mul_f32 v[126:127], v[116:117], v[156:157] op_sel:[1,0] op_sel_hi:[0,0]
	v_pk_mul_f32 v[172:173], v[112:113], v[158:159] op_sel:[1,0] op_sel_hi:[0,0]
	v_mov_b32_e32 v156, v153
	v_mul_f32_e32 v136, v119, v157
	v_mul_f32_e32 v168, v119, v153
	v_pk_mul_f32 v[170:171], v[112:113], v[154:155]
	v_mov_b32_e32 v158, v155
	v_mul_f32_e32 v174, v115, v159
	v_mul_f32_e32 v176, v115, v155
	v_pk_fma_f32 v[116:117], v[116:117], v[152:153], v[126:127] op_sel_hi:[1,0,1]
	v_mov_b32_e32 v152, v157
	v_pk_fma_f32 v[112:113], v[112:113], v[154:155], v[172:173] op_sel_hi:[1,0,1]
	v_mov_b32_e32 v154, v159
	v_pk_fma_f32 v[178:179], v[118:119], v[156:157], v[136:137] op_sel_hi:[1,1,0] neg_lo:[0,0,1] neg_hi:[0,0,1]
	v_pk_fma_f32 v[156:157], v[114:115], v[158:159], v[174:175] op_sel_hi:[1,1,0] neg_lo:[0,0,1] neg_hi:[0,0,1]
	v_pk_fma_f32 v[152:153], v[118:119], v[152:153], v[168:169] op_sel_hi:[1,1,0]
	v_pk_fma_f32 v[154:155], v[114:115], v[154:155], v[176:177] op_sel_hi:[1,1,0]
	v_sub_f32_e32 v112, v170, v172
	v_sub_f32_e32 v116, v122, v126
	v_mov_b32_e32 v114, v156
	v_mov_b32_e32 v118, v178
	v_mov_b32_e32 v115, v154
	v_mov_b32_e32 v119, v152
.LBB0_339:
	s_and_b32 s100, s51, 0xc0
	s_cmp_eq_u32 s100, 64
	s_cbranch_scc1 .Lp2a_norope1
	s_and_b32 s100, s51, 32
	s_lshl_b32 s100, s100, 1
	v_lshlrev_b32_e32 v202, 7, v148
	v_lshl_add_u32 v202, v162, 2, v202
	v_add_u32_e32 v202, s100, v202
	v_add_u32_e32 v202, 0x5000, v202
	global_load_dwordx4 v[190:193], v202, s[12:13] offset:2048
	global_load_dwordx4 v[194:197], v202, s[14:15] offset:2048
.Lp2a_norope1:
	s_ashr_i32 s1, s0, 31
	v_cvt_pk_bf16_f32 v116, v116, v117
	v_cvt_pk_bf16_f32 v117, v118, v119
	v_cvt_pk_bf16_f32 v118, v112, v113
	v_lshl_add_u64 v[112:113], s[0:1], 0, v[138:139]
	v_cvt_pk_bf16_f32 v119, v114, v115
	v_lshl_add_u64 v[114:115], v[112:113], 1, v[124:125]
	global_store_dwordx4 v[114:115], v[116:119], off offset:256
	s_andn2_b64 vcc, exec, s[8:9]
	s_nop 0
	v_or_b32_e32 v116, 16, v148
	v_ashrrev_i32_e32 v117, 31, v116
	v_lshl_add_u64 v[114:115], v[116:117], 2, s[44:45]
	s_nop 0
	v_cndmask_b32_e64 v114, 0, 1, s[8:9]
	v_cmp_ne_u32_e64 s[6:7], 1, v114
	v_lshlrev_b64 v[114:115], 5, v[116:117]
	v_lshlrev_b64 v[124:125], 2, v[114:115]
	v_lshl_add_u64 v[114:115], s[12:13], 0, v[124:125]
	v_mov_b32_e32 v118, v203
	v_fmamk_f32 v117, v118, 0x3b000000, v166
	v_mul_f32_e32 v118, 0x4b800000, v117
	v_cmp_gt_f32_e64 s[0:1], s94, v117
	s_nop 1
	v_cndmask_b32_e64 v117, v117, v118, s[0:1]
	v_rsq_f32_e32 v117, v117
	s_nop 0
	v_mul_f32_e32 v118, 0x45800000, v117
	v_cndmask_b32_e64 v117, v117, v118, s[0:1]
	v_mul_f32_e32 v118, 0x3dd53b94, v117
	v_pk_mul_f32 v[122:123], v[110:111], v[118:119] op_sel_hi:[1,0]
	v_pk_mul_f32 v[108:109], v[108:109], v[118:119] op_sel_hi:[1,0]
	v_pk_mul_f32 v[110:111], v[106:107], v[118:119] op_sel_hi:[1,0]
	v_pk_mul_f32 v[106:107], v[104:105], v[118:119] op_sel_hi:[1,0]
	v_lshl_add_u64 v[104:105], s[14:15], 0, v[124:125]
	s_cbranch_vccnz .LBB0_341
	s_add_i32 s0, s51, 0xffffff80
	s_lshr_b32 s0, s0, 1
	v_or_b32_e32 v136, s0, v162
	v_lshlrev_b64 v[124:125], 2, v[136:137]
	v_lshl_add_u64 v[126:127], v[114:115], 0, v[124:125]
	v_lshl_add_u64 v[152:153], v[104:105], 0, v[124:125]
	v_mov_b64_e32 v[124:125], v[198:199]
	v_mov_b64_e32 v[126:127], v[200:201]
	v_mov_b64_e32 v[152:153], v[206:207]
	v_mov_b64_e32 v[154:155], v[208:209]
	v_pk_mul_f32 v[156:157], v[108:109], v[124:125]
	v_pk_mul_f32 v[158:159], v[108:109], v[152:153] op_sel:[1,0] op_sel_hi:[0,0]
	v_pk_mul_f32 v[172:173], v[106:107], v[154:155] op_sel:[1,0] op_sel_hi:[0,0]
	v_mov_b32_e32 v152, v125
	v_mul_f32_e32 v136, v123, v153
	v_mul_f32_e32 v168, v123, v125
	v_pk_mul_f32 v[170:171], v[106:107], v[126:127]
	v_mov_b32_e32 v154, v127
	v_mul_f32_e32 v174, v111, v155
	v_mul_f32_e32 v176, v111, v127
	v_pk_fma_f32 v[108:109], v[108:109], v[124:125], v[158:159] op_sel_hi:[1,0,1]
	v_mov_b32_e32 v124, v153
	v_pk_fma_f32 v[106:107], v[106:107], v[126:127], v[172:173] op_sel_hi:[1,0,1]
	v_mov_b32_e32 v126, v155
	v_pk_fma_f32 v[178:179], v[122:123], v[152:153], v[136:137] op_sel_hi:[1,1,0] neg_lo:[0,0,1] neg_hi:[0,0,1]
	v_pk_fma_f32 v[152:153], v[110:111], v[154:155], v[174:175] op_sel_hi:[1,1,0] neg_lo:[0,0,1] neg_hi:[0,0,1]
	v_pk_fma_f32 v[124:125], v[122:123], v[124:125], v[168:169] op_sel_hi:[1,1,0]
	v_pk_fma_f32 v[126:127], v[110:111], v[126:127], v[176:177] op_sel_hi:[1,1,0]
	v_sub_f32_e32 v106, v170, v172
	v_sub_f32_e32 v108, v156, v158
	v_mov_b32_e32 v110, v152
	v_mov_b32_e32 v122, v178
	v_mov_b32_e32 v111, v126
	v_mov_b32_e32 v123, v124
.LBB0_341:
	v_cvt_pk_bf16_f32 v124, v108, v109
	v_cvt_pk_bf16_f32 v125, v122, v123
	v_cvt_pk_bf16_f32 v126, v106, v107
	v_mov_b64_e32 v[106:107], s[40:41]
	v_mad_i64_i32 v[106:107], s[0:1], v116, s95, v[106:107]
	v_lshl_add_u64 v[108:109], v[120:121], 1, v[106:107]
	v_cvt_pk_bf16_f32 v127, v110, v111
	global_store_dwordx4 v[108:109], v[124:127], off
	v_mov_b32_e32 v108, v118
	v_mov_b32_e32 v109, v118
	v_mov_b32_e32 v119, v118
	v_pk_mul_f32 v[102:103], v[102:103], v[108:109]
	v_pk_mul_f32 v[98:99], v[98:99], v[108:109]
	v_cndmask_b32_e64 v108, 0, 1, s[74:75]
	v_pk_mul_f32 v[100:101], v[100:101], v[118:119]
	v_cmp_ne_u32_e64 s[8:9], 1, v108
	s_andn2_b64 vcc, exec, s[74:75]
	v_pk_mul_f32 v[96:97], v[96:97], v[118:119]
	s_cbranch_vccnz .LBB0_343
	s_add_i32 s0, s53, 0xffffff80
	s_lshr_b32 s0, s0, 1
	v_or_b32_e32 v136, s0, v162
	v_lshlrev_b64 v[108:109], 2, v[136:137]
	v_lshl_add_u64 v[110:111], v[114:115], 0, v[108:109]
	v_lshl_add_u64 v[104:105], v[104:105], 0, v[108:109]
	v_mov_b64_e32 v[108:109], v[198:199]
	v_mov_b64_e32 v[110:111], v[200:201]
	v_mov_b64_e32 v[114:115], v[206:207]
	v_mov_b64_e32 v[116:117], v[208:209]
	v_pk_mul_f32 v[104:105], v[100:101], v[108:109]
	v_pk_mul_f32 v[118:119], v[100:101], v[114:115] op_sel:[1,0] op_sel_hi:[0,0]
	v_pk_mul_f32 v[152:153], v[96:97], v[116:117] op_sel:[1,0] op_sel_hi:[0,0]
	v_mov_b32_e32 v114, v109
	v_mul_f32_e32 v122, v103, v115
	v_mul_f32_e32 v124, v103, v109
	v_pk_mul_f32 v[126:127], v[96:97], v[110:111]
	v_mov_b32_e32 v116, v111
	v_mul_f32_e32 v136, v99, v117
	v_mul_f32_e32 v154, v99, v111
	v_pk_fma_f32 v[100:101], v[100:101], v[108:109], v[118:119] op_sel_hi:[1,0,1]
	v_mov_b32_e32 v108, v115
	v_pk_fma_f32 v[96:97], v[96:97], v[110:111], v[152:153] op_sel_hi:[1,0,1]
	v_mov_b32_e32 v110, v117
	v_pk_fma_f32 v[122:123], v[102:103], v[114:115], v[122:123] op_sel_hi:[1,1,0] neg_lo:[0,0,1] neg_hi:[0,0,1]
	v_pk_fma_f32 v[114:115], v[98:99], v[116:117], v[136:137] op_sel_hi:[1,1,0] neg_lo:[0,0,1] neg_hi:[0,0,1]
	v_pk_fma_f32 v[108:109], v[102:103], v[108:109], v[124:125] op_sel_hi:[1,1,0]
	v_pk_fma_f32 v[110:111], v[98:99], v[110:111], v[154:155] op_sel_hi:[1,1,0]
	v_sub_f32_e32 v96, v126, v152
	v_sub_f32_e32 v100, v104, v118
	v_mov_b32_e32 v98, v114
	v_mov_b32_e32 v102, v122
	v_mov_b32_e32 v99, v110
	v_mov_b32_e32 v103, v108
.LBB0_343:
	v_cvt_pk_bf16_f32 v100, v100, v101
	v_cvt_pk_bf16_f32 v101, v102, v103
	v_cvt_pk_bf16_f32 v102, v96, v97
	v_cvt_pk_bf16_f32 v103, v98, v99
	v_or_b32_e32 v98, 32, v148
	v_lshl_add_u64 v[96:97], v[112:113], 1, v[106:107]
	v_ashrrev_i32_e32 v99, 31, v98
	global_store_dwordx4 v[96:97], v[100:103], off offset:256
	v_lshl_add_u64 v[96:97], v[98:99], 2, s[44:45]
	s_nop 0
	s_and_b64 vcc, exec, s[6:7]
	v_mov_b32_e32 v96, v230
	v_fmamk_f32 v96, v96, 0x3b000000, v166
	v_mul_f32_e32 v97, 0x4b800000, v96
	v_cmp_gt_f32_e64 s[0:1], s94, v96
	s_nop 1
	v_cndmask_b32_e64 v96, v96, v97, s[0:1]
	v_rsq_f32_e32 v100, v96
	v_lshlrev_b64 v[96:97], 5, v[98:99]
	v_lshlrev_b64 v[104:105], 2, v[96:97]
	v_lshl_add_u64 v[96:97], s[12:13], 0, v[104:105]
	v_mul_f32_e32 v99, 0x45800000, v100
	v_cndmask_b32_e64 v99, v100, v99, s[0:1]
	v_mul_f32_e32 v100, 0x3dd53b94, v99
	v_pk_mul_f32 v[102:103], v[94:95], v[100:101] op_sel_hi:[1,0]
	v_pk_mul_f32 v[92:93], v[92:93], v[100:101] op_sel_hi:[1,0]
	v_pk_mul_f32 v[94:95], v[90:91], v[100:101] op_sel_hi:[1,0]
	v_pk_mul_f32 v[90:91], v[88:89], v[100:101] op_sel_hi:[1,0]
	v_lshl_add_u64 v[88:89], s[14:15], 0, v[104:105]
	s_cbranch_vccnz .LBB0_345
	s_add_i32 s0, s51, 0xffffff80
	s_lshr_b32 s0, s0, 1
	v_or_b32_e32 v136, s0, v162
	v_lshlrev_b64 v[104:105], 2, v[136:137]
	v_lshl_add_u64 v[106:107], v[96:97], 0, v[104:105]
	v_lshl_add_u64 v[108:109], v[88:89], 0, v[104:105]
	v_mov_b64_e32 v[104:105], v[210:211]
	v_mov_b64_e32 v[106:107], v[212:213]
	v_mov_b64_e32 v[108:109], v[214:215]
	v_mov_b64_e32 v[110:111], v[216:217]
	v_pk_mul_f32 v[114:115], v[92:93], v[104:105]
	v_pk_mul_f32 v[116:117], v[92:93], v[108:109] op_sel:[1,0] op_sel_hi:[0,0]
	v_pk_mul_f32 v[126:127], v[90:91], v[110:111] op_sel:[1,0] op_sel_hi:[0,0]
	v_mov_b32_e32 v108, v105
	v_mul_f32_e32 v118, v103, v109
	v_mul_f32_e32 v122, v103, v105
	v_pk_mul_f32 v[124:125], v[90:91], v[106:107]
	v_mov_b32_e32 v110, v107
	v_mul_f32_e32 v136, v95, v111
	v_mul_f32_e32 v152, v95, v107
	v_pk_fma_f32 v[92:93], v[92:93], v[104:105], v[116:117] op_sel_hi:[1,0,1]
	v_mov_b32_e32 v104, v109
	v_pk_fma_f32 v[90:91], v[90:91], v[106:107], v[126:127] op_sel_hi:[1,0,1]
	v_mov_b32_e32 v106, v111
	v_pk_fma_f32 v[118:119], v[102:103], v[108:109], v[118:119] op_sel_hi:[1,1,0] neg_lo:[0,0,1] neg_hi:[0,0,1]
	v_pk_fma_f32 v[108:109], v[94:95], v[110:111], v[136:137] op_sel_hi:[1,1,0] neg_lo:[0,0,1] neg_hi:[0,0,1]
	v_pk_fma_f32 v[104:105], v[102:103], v[104:105], v[122:123] op_sel_hi:[1,1,0]
	v_pk_fma_f32 v[106:107], v[94:95], v[106:107], v[152:153] op_sel_hi:[1,1,0]
	v_sub_f32_e32 v90, v124, v126
	v_sub_f32_e32 v92, v114, v116
	v_mov_b32_e32 v94, v108
	v_mov_b32_e32 v102, v118
	v_mov_b32_e32 v95, v106
	v_mov_b32_e32 v103, v104
.LBB0_345:
	v_cvt_pk_bf16_f32 v104, v92, v93
	v_cvt_pk_bf16_f32 v105, v102, v103
	v_cvt_pk_bf16_f32 v106, v90, v91
	v_mov_b64_e32 v[90:91], s[40:41]
	v_mad_i64_i32 v[90:91], s[0:1], v98, s95, v[90:91]
	v_lshl_add_u64 v[92:93], v[120:121], 1, v[90:91]
	v_mov_b32_e32 v101, v100
	v_cvt_pk_bf16_f32 v107, v94, v95
	global_store_dwordx4 v[92:93], v[104:107], off
	v_mov_b32_e32 v92, v100
	v_mov_b32_e32 v93, v100
	v_pk_mul_f32 v[86:87], v[86:87], v[92:93]
	v_pk_mul_f32 v[84:85], v[84:85], v[100:101]
	v_pk_mul_f32 v[82:83], v[82:83], v[92:93]
	s_and_b64 vcc, exec, s[8:9]
	v_pk_mul_f32 v[80:81], v[80:81], v[100:101]
	s_cbranch_vccnz .LBB0_347
	s_add_i32 s0, s53, 0xffffff80
	s_lshr_b32 s0, s0, 1
	v_or_b32_e32 v136, s0, v162
	v_lshlrev_b64 v[92:93], 2, v[136:137]
	v_lshl_add_u64 v[94:95], v[96:97], 0, v[92:93]
	v_lshl_add_u64 v[88:89], v[88:89], 0, v[92:93]
	v_mov_b64_e32 v[92:93], v[210:211]
	v_mov_b64_e32 v[94:95], v[212:213]
	v_mov_b64_e32 v[96:97], v[214:215]
	v_mov_b64_e32 v[98:99], v[216:217]
	v_pk_mul_f32 v[88:89], v[84:85], v[92:93]
	v_pk_mul_f32 v[100:101], v[84:85], v[96:97] op_sel:[1,0] op_sel_hi:[0,0]
	v_pk_mul_f32 v[108:109], v[80:81], v[98:99] op_sel:[1,0] op_sel_hi:[0,0]
	v_mov_b32_e32 v96, v93
	v_mul_f32_e32 v102, v87, v97
	v_mul_f32_e32 v104, v87, v93
	v_pk_mul_f32 v[106:107], v[80:81], v[94:95]
	v_mov_b32_e32 v98, v95
	v_mul_f32_e32 v110, v83, v99
	v_mul_f32_e32 v114, v83, v95
	v_pk_fma_f32 v[84:85], v[84:85], v[92:93], v[100:101] op_sel_hi:[1,0,1]
	v_mov_b32_e32 v92, v97
	v_pk_fma_f32 v[80:81], v[80:81], v[94:95], v[108:109] op_sel_hi:[1,0,1]
	v_mov_b32_e32 v94, v99
	v_pk_fma_f32 v[102:103], v[86:87], v[96:97], v[102:103] op_sel_hi:[1,1,0] neg_lo:[0,0,1] neg_hi:[0,0,1]
	v_pk_fma_f32 v[96:97], v[82:83], v[98:99], v[110:111] op_sel_hi:[1,1,0] neg_lo:[0,0,1] neg_hi:[0,0,1]
	v_pk_fma_f32 v[92:93], v[86:87], v[92:93], v[104:105] op_sel_hi:[1,1,0]
	v_pk_fma_f32 v[94:95], v[82:83], v[94:95], v[114:115] op_sel_hi:[1,1,0]
	v_sub_f32_e32 v80, v106, v108
	v_sub_f32_e32 v84, v88, v100
	v_mov_b32_e32 v82, v96
	v_mov_b32_e32 v86, v102
	v_mov_b32_e32 v83, v94
	v_mov_b32_e32 v87, v92
.LBB0_347:
	v_cvt_pk_bf16_f32 v84, v84, v85
	v_cvt_pk_bf16_f32 v85, v86, v87
	v_cvt_pk_bf16_f32 v86, v80, v81
	v_cvt_pk_bf16_f32 v87, v82, v83
	v_or_b32_e32 v82, 48, v148
	v_lshl_add_u64 v[80:81], v[112:113], 1, v[90:91]
	v_ashrrev_i32_e32 v83, 31, v82
	global_store_dwordx4 v[80:81], v[84:87], off offset:256
	v_lshl_add_u64 v[80:81], v[82:83], 2, s[44:45]
	s_nop 0
	s_and_b64 vcc, exec, s[6:7]
	v_mov_b32_e32 v80, v231
	v_fmamk_f32 v80, v80, 0x3b000000, v166
	v_mul_f32_e32 v81, 0x4b800000, v80
	v_cmp_gt_f32_e64 s[0:1], s94, v80
	s_nop 1
	v_cndmask_b32_e64 v80, v80, v81, s[0:1]
	v_rsq_f32_e32 v84, v80
	v_lshlrev_b64 v[80:81], 5, v[82:83]
	v_lshlrev_b64 v[88:89], 2, v[80:81]
	v_lshl_add_u64 v[80:81], s[12:13], 0, v[88:89]
	v_mul_f32_e32 v83, 0x45800000, v84
	v_cndmask_b32_e64 v83, v84, v83, s[0:1]
	v_mul_f32_e32 v84, 0x3dd53b94, v83
	v_pk_mul_f32 v[86:87], v[78:79], v[84:85] op_sel_hi:[1,0]
	v_pk_mul_f32 v[76:77], v[76:77], v[84:85] op_sel_hi:[1,0]
	v_pk_mul_f32 v[78:79], v[74:75], v[84:85] op_sel_hi:[1,0]
	v_pk_mul_f32 v[74:75], v[72:73], v[84:85] op_sel_hi:[1,0]
	v_lshl_add_u64 v[72:73], s[14:15], 0, v[88:89]
	s_cbranch_vccnz .LBB0_349
	s_add_i32 s0, s51, 0xffffff80
	s_lshr_b32 s0, s0, 1
	v_or_b32_e32 v136, s0, v162
	v_lshlrev_b64 v[88:89], 2, v[136:137]
	v_lshl_add_u64 v[90:91], v[80:81], 0, v[88:89]
	v_lshl_add_u64 v[92:93], v[72:73], 0, v[88:89]
	v_mov_b64_e32 v[88:89], v[218:219]
	v_mov_b64_e32 v[90:91], v[220:221]
	v_mov_b64_e32 v[92:93], v[222:223]
	v_mov_b64_e32 v[94:95], v[224:225]
	v_pk_mul_f32 v[96:97], v[76:77], v[88:89]
	v_pk_mul_f32 v[98:99], v[76:77], v[92:93] op_sel:[1,0] op_sel_hi:[0,0]
	v_pk_mul_f32 v[106:107], v[74:75], v[94:95] op_sel:[1,0] op_sel_hi:[0,0]
	v_mov_b32_e32 v92, v89
	v_mul_f32_e32 v100, v87, v93
	v_mul_f32_e32 v102, v87, v89
	v_pk_mul_f32 v[104:105], v[74:75], v[90:91]
	v_mov_b32_e32 v94, v91
	v_mul_f32_e32 v108, v79, v95
	v_mul_f32_e32 v110, v79, v91
	v_pk_fma_f32 v[76:77], v[76:77], v[88:89], v[98:99] op_sel_hi:[1,0,1]
	v_mov_b32_e32 v88, v93
	v_pk_fma_f32 v[74:75], v[74:75], v[90:91], v[106:107] op_sel_hi:[1,0,1]
	v_mov_b32_e32 v90, v95
	v_pk_fma_f32 v[100:101], v[86:87], v[92:93], v[100:101] op_sel_hi:[1,1,0] neg_lo:[0,0,1] neg_hi:[0,0,1]
	v_pk_fma_f32 v[92:93], v[78:79], v[94:95], v[108:109] op_sel_hi:[1,1,0] neg_lo:[0,0,1] neg_hi:[0,0,1]
	v_pk_fma_f32 v[88:89], v[86:87], v[88:89], v[102:103] op_sel_hi:[1,1,0]
	v_pk_fma_f32 v[90:91], v[78:79], v[90:91], v[110:111] op_sel_hi:[1,1,0]
	v_sub_f32_e32 v74, v104, v106
	v_sub_f32_e32 v76, v96, v98
	v_mov_b32_e32 v78, v92
	v_mov_b32_e32 v86, v100
	v_mov_b32_e32 v79, v90
	v_mov_b32_e32 v87, v88
.LBB0_349:
	v_cvt_pk_bf16_f32 v88, v76, v77
	v_cvt_pk_bf16_f32 v89, v86, v87
	v_cvt_pk_bf16_f32 v90, v74, v75
	v_mov_b64_e32 v[74:75], s[40:41]
	v_mad_i64_i32 v[74:75], s[0:1], v82, s95, v[74:75]
	v_lshl_add_u64 v[76:77], v[120:121], 1, v[74:75]
	v_mov_b32_e32 v85, v84
	v_cvt_pk_bf16_f32 v91, v78, v79
	global_store_dwordx4 v[76:77], v[88:91], off
	v_mov_b32_e32 v76, v84
	v_mov_b32_e32 v77, v84
	v_pk_mul_f32 v[70:71], v[70:71], v[76:77]
	v_pk_mul_f32 v[68:69], v[68:69], v[84:85]
	v_pk_mul_f32 v[66:67], v[66:67], v[76:77]
	s_and_b64 vcc, exec, s[8:9]
	v_pk_mul_f32 v[64:65], v[64:65], v[84:85]
	s_cbranch_vccnz .LBB0_351
	s_add_i32 s0, s53, 0xffffff80
	s_lshr_b32 s0, s0, 1
	v_or_b32_e32 v136, s0, v162
	v_lshlrev_b64 v[76:77], 2, v[136:137]
	v_lshl_add_u64 v[78:79], v[80:81], 0, v[76:77]
	v_lshl_add_u64 v[72:73], v[72:73], 0, v[76:77]
	v_mov_b64_e32 v[76:77], v[218:219]
	v_mov_b64_e32 v[78:79], v[220:221]
	v_mov_b64_e32 v[80:81], v[222:223]
	v_mov_b64_e32 v[82:83], v[224:225]
	v_pk_mul_f32 v[72:73], v[68:69], v[76:77]
	v_pk_mul_f32 v[84:85], v[68:69], v[80:81] op_sel:[1,0] op_sel_hi:[0,0]
	v_pk_mul_f32 v[92:93], v[64:65], v[82:83] op_sel:[1,0] op_sel_hi:[0,0]
	v_mov_b32_e32 v80, v77
	v_mul_f32_e32 v86, v71, v81
	v_mul_f32_e32 v88, v71, v77
	v_pk_mul_f32 v[90:91], v[64:65], v[78:79]
	v_mov_b32_e32 v82, v79
	v_mul_f32_e32 v94, v67, v83
	v_mul_f32_e32 v96, v67, v79
	v_pk_fma_f32 v[68:69], v[68:69], v[76:77], v[84:85] op_sel_hi:[1,0,1]
	v_mov_b32_e32 v76, v81
	v_pk_fma_f32 v[64:65], v[64:65], v[78:79], v[92:93] op_sel_hi:[1,0,1]
	v_mov_b32_e32 v78, v83
	v_pk_fma_f32 v[86:87], v[70:71], v[80:81], v[86:87] op_sel_hi:[1,1,0] neg_lo:[0,0,1] neg_hi:[0,0,1]
	v_pk_fma_f32 v[80:81], v[66:67], v[82:83], v[94:95] op_sel_hi:[1,1,0] neg_lo:[0,0,1] neg_hi:[0,0,1]
	v_pk_fma_f32 v[76:77], v[70:71], v[76:77], v[88:89] op_sel_hi:[1,1,0]
	v_pk_fma_f32 v[78:79], v[66:67], v[78:79], v[96:97] op_sel_hi:[1,1,0]
	v_sub_f32_e32 v64, v90, v92
	v_sub_f32_e32 v68, v72, v84
	v_mov_b32_e32 v66, v80
	v_mov_b32_e32 v70, v86
	v_mov_b32_e32 v67, v78
	v_mov_b32_e32 v71, v76
.LBB0_351:
	v_cvt_pk_bf16_f32 v68, v68, v69
	v_cvt_pk_bf16_f32 v69, v70, v71
	v_cvt_pk_bf16_f32 v70, v64, v65
	v_lshl_add_u64 v[64:65], v[112:113], 1, v[74:75]
	v_cvt_pk_bf16_f32 v71, v66, v67
	global_store_dwordx4 v[64:65], v[68:71], off offset:256
	s_nop 0
	v_add_u32_e32 v66, 0x80, v148
	v_ashrrev_i32_e32 v67, 31, v66
	s_and_b64 vcc, exec, s[6:7]
	v_mov_b32_e32 v64, v252
	v_fmamk_f32 v64, v64, 0x3b000000, v166
	v_mul_f32_e32 v65, 0x4b800000, v64
	v_cmp_gt_f32_e64 s[0:1], s94, v64
	s_nop 1
	v_cndmask_b32_e64 v64, v64, v65, s[0:1]
	v_rsq_f32_e32 v68, v64
	v_lshlrev_b64 v[64:65], 5, v[66:67]
	v_lshlrev_b64 v[72:73], 2, v[64:65]
	v_lshl_add_u64 v[64:65], s[12:13], 0, v[72:73]
	v_mul_f32_e32 v67, 0x45800000, v68
	v_cndmask_b32_e64 v67, v68, v67, s[0:1]
	v_mul_f32_e32 v68, 0x3dd53b94, v67
	v_pk_mul_f32 v[70:71], v[62:63], v[68:69] op_sel_hi:[1,0]
	v_pk_mul_f32 v[60:61], v[60:61], v[68:69] op_sel_hi:[1,0]
	v_pk_mul_f32 v[62:63], v[58:59], v[68:69] op_sel_hi:[1,0]
	v_pk_mul_f32 v[58:59], v[56:57], v[68:69] op_sel_hi:[1,0]
	v_lshl_add_u64 v[56:57], s[14:15], 0, v[72:73]
	s_cbranch_vccnz .LBB0_353
	s_add_i32 s0, s51, 0xffffff80
	s_lshr_b32 s0, s0, 1
	v_or_b32_e32 v136, s0, v162
	v_lshlrev_b64 v[72:73], 2, v[136:137]
	v_lshl_add_u64 v[74:75], v[64:65], 0, v[72:73]
	v_lshl_add_u64 v[76:77], v[56:57], 0, v[72:73]
	v_mov_b64_e32 v[72:73], v[226:227]
	v_mov_b64_e32 v[74:75], v[228:229]
	v_mov_b64_e32 v[76:77], v[232:233]
	v_mov_b64_e32 v[78:79], v[234:235]
	v_pk_mul_f32 v[80:81], v[60:61], v[72:73]
	v_pk_mul_f32 v[82:83], v[60:61], v[76:77] op_sel:[1,0] op_sel_hi:[0,0]
	v_pk_mul_f32 v[90:91], v[58:59], v[78:79] op_sel:[1,0] op_sel_hi:[0,0]
	v_mov_b32_e32 v76, v73
	v_mul_f32_e32 v84, v71, v77
	v_mul_f32_e32 v86, v71, v73
	v_pk_mul_f32 v[88:89], v[58:59], v[74:75]
	v_mov_b32_e32 v78, v75
	v_mul_f32_e32 v92, v63, v79
	v_mul_f32_e32 v94, v63, v75
	v_pk_fma_f32 v[60:61], v[60:61], v[72:73], v[82:83] op_sel_hi:[1,0,1]
	v_mov_b32_e32 v72, v77
	v_pk_fma_f32 v[58:59], v[58:59], v[74:75], v[90:91] op_sel_hi:[1,0,1]
	v_mov_b32_e32 v74, v79
	v_pk_fma_f32 v[84:85], v[70:71], v[76:77], v[84:85] op_sel_hi:[1,1,0] neg_lo:[0,0,1] neg_hi:[0,0,1]
	v_pk_fma_f32 v[76:77], v[62:63], v[78:79], v[92:93] op_sel_hi:[1,1,0] neg_lo:[0,0,1] neg_hi:[0,0,1]
	v_pk_fma_f32 v[72:73], v[70:71], v[72:73], v[86:87] op_sel_hi:[1,1,0]
	v_pk_fma_f32 v[74:75], v[62:63], v[74:75], v[94:95] op_sel_hi:[1,1,0]
	v_sub_f32_e32 v58, v88, v90
	v_sub_f32_e32 v60, v80, v82
	v_mov_b32_e32 v62, v76
	v_mov_b32_e32 v70, v84
	v_mov_b32_e32 v63, v74
	v_mov_b32_e32 v71, v72
.LBB0_353:
	v_cvt_pk_bf16_f32 v72, v60, v61
	v_cvt_pk_bf16_f32 v73, v70, v71
	v_cvt_pk_bf16_f32 v74, v58, v59
	v_mov_b64_e32 v[58:59], s[40:41]
	v_mad_i64_i32 v[58:59], s[0:1], v66, s95, v[58:59]
	v_lshl_add_u64 v[60:61], v[120:121], 1, v[58:59]
	v_mov_b32_e32 v69, v68
	v_cvt_pk_bf16_f32 v75, v62, v63
	global_store_dwordx4 v[60:61], v[72:75], off
	v_mov_b32_e32 v60, v68
	v_mov_b32_e32 v61, v68
	v_pk_mul_f32 v[54:55], v[54:55], v[60:61]
	v_pk_mul_f32 v[52:53], v[52:53], v[68:69]
	v_pk_mul_f32 v[50:51], v[50:51], v[60:61]
	s_and_b64 vcc, exec, s[8:9]
	v_pk_mul_f32 v[48:49], v[48:49], v[68:69]
	s_cbranch_vccnz .LBB0_355
	s_add_i32 s0, s53, 0xffffff80
	s_lshr_b32 s0, s0, 1
	v_or_b32_e32 v136, s0, v162
	v_lshlrev_b64 v[60:61], 2, v[136:137]
	v_lshl_add_u64 v[62:63], v[64:65], 0, v[60:61]
	v_lshl_add_u64 v[56:57], v[56:57], 0, v[60:61]
	v_mov_b64_e32 v[60:61], v[226:227]
	v_mov_b64_e32 v[62:63], v[228:229]
	v_mov_b64_e32 v[64:65], v[232:233]
	v_mov_b64_e32 v[66:67], v[234:235]
	v_pk_mul_f32 v[56:57], v[52:53], v[60:61]
	v_pk_mul_f32 v[68:69], v[52:53], v[64:65] op_sel:[1,0] op_sel_hi:[0,0]
	v_pk_mul_f32 v[76:77], v[48:49], v[66:67] op_sel:[1,0] op_sel_hi:[0,0]
	v_mov_b32_e32 v64, v61
	v_mul_f32_e32 v70, v55, v65
	v_mul_f32_e32 v72, v55, v61
	v_pk_mul_f32 v[74:75], v[48:49], v[62:63]
	v_mov_b32_e32 v66, v63
	v_mul_f32_e32 v78, v51, v67
	v_mul_f32_e32 v80, v51, v63
	v_pk_fma_f32 v[52:53], v[52:53], v[60:61], v[68:69] op_sel_hi:[1,0,1]
	v_mov_b32_e32 v60, v65
	v_pk_fma_f32 v[48:49], v[48:49], v[62:63], v[76:77] op_sel_hi:[1,0,1]
	v_mov_b32_e32 v62, v67
	v_pk_fma_f32 v[70:71], v[54:55], v[64:65], v[70:71] op_sel_hi:[1,1,0] neg_lo:[0,0,1] neg_hi:[0,0,1]
	v_pk_fma_f32 v[64:65], v[50:51], v[66:67], v[78:79] op_sel_hi:[1,1,0] neg_lo:[0,0,1] neg_hi:[0,0,1]
	v_pk_fma_f32 v[60:61], v[54:55], v[60:61], v[72:73] op_sel_hi:[1,1,0]
	v_pk_fma_f32 v[62:63], v[50:51], v[62:63], v[80:81] op_sel_hi:[1,1,0]
	v_sub_f32_e32 v48, v74, v76
	v_sub_f32_e32 v52, v56, v68
	v_mov_b32_e32 v50, v64
	v_mov_b32_e32 v54, v70
	v_mov_b32_e32 v51, v62
	v_mov_b32_e32 v55, v60
.LBB0_355:
	v_cvt_pk_bf16_f32 v52, v52, v53
	v_cvt_pk_bf16_f32 v53, v54, v55
	v_cvt_pk_bf16_f32 v54, v48, v49
	v_lshl_add_u64 v[48:49], v[112:113], 1, v[58:59]
	v_cvt_pk_bf16_f32 v55, v50, v51
	global_store_dwordx4 v[48:49], v[52:55], off offset:256
	s_nop 0
	v_add_u32_e32 v50, 0x90, v148
	v_ashrrev_i32_e32 v51, 31, v50
	s_and_b64 vcc, exec, s[6:7]
	v_mov_b32_e32 v48, v253
	v_fmamk_f32 v48, v48, 0x3b000000, v166
	v_mul_f32_e32 v49, 0x4b800000, v48
	v_cmp_gt_f32_e64 s[0:1], s94, v48
	s_nop 1
	v_cndmask_b32_e64 v48, v48, v49, s[0:1]
	v_rsq_f32_e32 v52, v48
	v_lshlrev_b64 v[48:49], 5, v[50:51]
	v_lshlrev_b64 v[56:57], 2, v[48:49]
	v_lshl_add_u64 v[48:49], s[12:13], 0, v[56:57]
	v_mul_f32_e32 v51, 0x45800000, v52
	v_cndmask_b32_e64 v51, v52, v51, s[0:1]
	v_mul_f32_e32 v52, 0x3dd53b94, v51
	v_pk_mul_f32 v[54:55], v[46:47], v[52:53] op_sel_hi:[1,0]
	v_pk_mul_f32 v[44:45], v[44:45], v[52:53] op_sel_hi:[1,0]
	v_pk_mul_f32 v[46:47], v[42:43], v[52:53] op_sel_hi:[1,0]
	v_pk_mul_f32 v[42:43], v[40:41], v[52:53] op_sel_hi:[1,0]
	v_lshl_add_u64 v[40:41], s[14:15], 0, v[56:57]
	s_cbranch_vccnz .LBB0_357
	s_add_i32 s0, s51, 0xffffff80
	s_lshr_b32 s0, s0, 1
	v_or_b32_e32 v136, s0, v162
	v_lshlrev_b64 v[56:57], 2, v[136:137]
	v_lshl_add_u64 v[58:59], v[48:49], 0, v[56:57]
	v_lshl_add_u64 v[60:61], v[40:41], 0, v[56:57]
	v_mov_b64_e32 v[56:57], v[236:237]
	v_mov_b64_e32 v[58:59], v[238:239]
	v_mov_b64_e32 v[60:61], v[240:241]
	v_mov_b64_e32 v[62:63], v[242:243]
	v_pk_mul_f32 v[64:65], v[44:45], v[56:57]
	v_pk_mul_f32 v[66:67], v[44:45], v[60:61] op_sel:[1,0] op_sel_hi:[0,0]
	v_pk_mul_f32 v[74:75], v[42:43], v[62:63] op_sel:[1,0] op_sel_hi:[0,0]
	v_mov_b32_e32 v60, v57
	v_mul_f32_e32 v68, v55, v61
	v_mul_f32_e32 v70, v55, v57
	v_pk_mul_f32 v[72:73], v[42:43], v[58:59]
	v_mov_b32_e32 v62, v59
	v_mul_f32_e32 v76, v47, v63
	v_mul_f32_e32 v78, v47, v59
	v_pk_fma_f32 v[44:45], v[44:45], v[56:57], v[66:67] op_sel_hi:[1,0,1]
	v_mov_b32_e32 v56, v61
	v_pk_fma_f32 v[42:43], v[42:43], v[58:59], v[74:75] op_sel_hi:[1,0,1]
	v_mov_b32_e32 v58, v63
	v_pk_fma_f32 v[68:69], v[54:55], v[60:61], v[68:69] op_sel_hi:[1,1,0] neg_lo:[0,0,1] neg_hi:[0,0,1]
	v_pk_fma_f32 v[60:61], v[46:47], v[62:63], v[76:77] op_sel_hi:[1,1,0] neg_lo:[0,0,1] neg_hi:[0,0,1]
	v_pk_fma_f32 v[56:57], v[54:55], v[56:57], v[70:71] op_sel_hi:[1,1,0]
	v_pk_fma_f32 v[58:59], v[46:47], v[58:59], v[78:79] op_sel_hi:[1,1,0]
	v_sub_f32_e32 v42, v72, v74
	v_sub_f32_e32 v44, v64, v66
	v_mov_b32_e32 v46, v60
	v_mov_b32_e32 v54, v68
	v_mov_b32_e32 v47, v58
	v_mov_b32_e32 v55, v56
.LBB0_357:
	v_cvt_pk_bf16_f32 v56, v44, v45
	v_cvt_pk_bf16_f32 v57, v54, v55
	v_cvt_pk_bf16_f32 v58, v42, v43
	v_mov_b64_e32 v[42:43], s[40:41]
	v_mad_i64_i32 v[42:43], s[0:1], v50, s95, v[42:43]
	v_lshl_add_u64 v[44:45], v[120:121], 1, v[42:43]
	v_mov_b32_e32 v53, v52
	v_cvt_pk_bf16_f32 v59, v46, v47
	global_store_dwordx4 v[44:45], v[56:59], off
	v_mov_b32_e32 v44, v52
	v_mov_b32_e32 v45, v52
	v_pk_mul_f32 v[38:39], v[38:39], v[44:45]
	v_pk_mul_f32 v[36:37], v[36:37], v[52:53]
	v_pk_mul_f32 v[34:35], v[34:35], v[44:45]
	s_and_b64 vcc, exec, s[8:9]
	v_pk_mul_f32 v[32:33], v[32:33], v[52:53]
	s_cbranch_vccnz .LBB0_359
	s_add_i32 s0, s53, 0xffffff80
	s_lshr_b32 s0, s0, 1
	v_or_b32_e32 v136, s0, v162
	v_lshlrev_b64 v[44:45], 2, v[136:137]
	v_lshl_add_u64 v[46:47], v[48:49], 0, v[44:45]
	v_lshl_add_u64 v[40:41], v[40:41], 0, v[44:45]
	v_mov_b64_e32 v[44:45], v[236:237]
	v_mov_b64_e32 v[46:47], v[238:239]
	v_mov_b64_e32 v[48:49], v[240:241]
	v_mov_b64_e32 v[50:51], v[242:243]
	v_pk_mul_f32 v[40:41], v[36:37], v[44:45]
	v_pk_mul_f32 v[52:53], v[36:37], v[48:49] op_sel:[1,0] op_sel_hi:[0,0]
	v_pk_mul_f32 v[60:61], v[32:33], v[50:51] op_sel:[1,0] op_sel_hi:[0,0]
	v_mov_b32_e32 v48, v45
	v_mul_f32_e32 v54, v39, v49
	v_mul_f32_e32 v56, v39, v45
	v_pk_mul_f32 v[58:59], v[32:33], v[46:47]
	v_mov_b32_e32 v50, v47
	v_mul_f32_e32 v62, v35, v51
	v_mul_f32_e32 v64, v35, v47
	v_pk_fma_f32 v[36:37], v[36:37], v[44:45], v[52:53] op_sel_hi:[1,0,1]
	v_mov_b32_e32 v44, v49
	v_pk_fma_f32 v[32:33], v[32:33], v[46:47], v[60:61] op_sel_hi:[1,0,1]
	v_mov_b32_e32 v46, v51
	v_pk_fma_f32 v[54:55], v[38:39], v[48:49], v[54:55] op_sel_hi:[1,1,0] neg_lo:[0,0,1] neg_hi:[0,0,1]
	v_pk_fma_f32 v[48:49], v[34:35], v[50:51], v[62:63] op_sel_hi:[1,1,0] neg_lo:[0,0,1] neg_hi:[0,0,1]
	v_pk_fma_f32 v[44:45], v[38:39], v[44:45], v[56:57] op_sel_hi:[1,1,0]
	v_pk_fma_f32 v[46:47], v[34:35], v[46:47], v[64:65] op_sel_hi:[1,1,0]
	v_sub_f32_e32 v32, v58, v60
	v_sub_f32_e32 v36, v40, v52
	v_mov_b32_e32 v34, v48
	v_mov_b32_e32 v38, v54
	v_mov_b32_e32 v35, v46
	v_mov_b32_e32 v39, v44
.LBB0_359:
	v_cvt_pk_bf16_f32 v36, v36, v37
	v_cvt_pk_bf16_f32 v37, v38, v39
	v_cvt_pk_bf16_f32 v38, v32, v33
	v_lshl_add_u64 v[32:33], v[112:113], 1, v[42:43]
	v_cvt_pk_bf16_f32 v39, v34, v35
	global_store_dwordx4 v[32:33], v[36:39], off offset:256
	s_nop 0
	v_add_u32_e32 v34, 0xa0, v148
	v_ashrrev_i32_e32 v35, 31, v34
	s_and_b64 vcc, exec, s[6:7]
	v_mov_b32_e32 v32, v255
	v_fmamk_f32 v32, v32, 0x3b000000, v166
	v_mul_f32_e32 v33, 0x4b800000, v32
	v_cmp_gt_f32_e64 s[0:1], s94, v32
	s_nop 1
	v_cndmask_b32_e64 v32, v32, v33, s[0:1]
	v_rsq_f32_e32 v36, v32
	v_lshlrev_b64 v[32:33], 5, v[34:35]
	v_lshlrev_b64 v[40:41], 2, v[32:33]
	v_lshl_add_u64 v[32:33], s[12:13], 0, v[40:41]
	v_mul_f32_e32 v35, 0x45800000, v36
	v_cndmask_b32_e64 v35, v36, v35, s[0:1]
	v_mul_f32_e32 v36, 0x3dd53b94, v35
	v_pk_mul_f32 v[38:39], v[30:31], v[36:37] op_sel_hi:[1,0]
	v_pk_mul_f32 v[28:29], v[28:29], v[36:37] op_sel_hi:[1,0]
	v_pk_mul_f32 v[30:31], v[26:27], v[36:37] op_sel_hi:[1,0]
	v_pk_mul_f32 v[26:27], v[24:25], v[36:37] op_sel_hi:[1,0]
	v_lshl_add_u64 v[24:25], s[14:15], 0, v[40:41]
	s_cbranch_vccnz .LBB0_361
	s_add_i32 s0, s51, 0xffffff80
	s_lshr_b32 s0, s0, 1
	v_or_b32_e32 v136, s0, v162
	v_lshlrev_b64 v[40:41], 2, v[136:137]
	v_lshl_add_u64 v[42:43], v[32:33], 0, v[40:41]
	v_lshl_add_u64 v[44:45], v[24:25], 0, v[40:41]
	v_mov_b64_e32 v[40:41], v[244:245]
	v_mov_b64_e32 v[42:43], v[246:247]
	v_mov_b64_e32 v[44:45], v[248:249]
	v_mov_b64_e32 v[46:47], v[250:251]
	v_pk_mul_f32 v[48:49], v[28:29], v[40:41]
	v_pk_mul_f32 v[50:51], v[28:29], v[44:45] op_sel:[1,0] op_sel_hi:[0,0]
	v_pk_mul_f32 v[58:59], v[26:27], v[46:47] op_sel:[1,0] op_sel_hi:[0,0]
	v_mov_b32_e32 v44, v41
	v_mul_f32_e32 v52, v39, v45
	v_mul_f32_e32 v54, v39, v41
	v_pk_mul_f32 v[56:57], v[26:27], v[42:43]
	v_mov_b32_e32 v46, v43
	v_mul_f32_e32 v60, v31, v47
	v_mul_f32_e32 v62, v31, v43
	v_pk_fma_f32 v[28:29], v[28:29], v[40:41], v[50:51] op_sel_hi:[1,0,1]
	v_mov_b32_e32 v40, v45
	v_pk_fma_f32 v[26:27], v[26:27], v[42:43], v[58:59] op_sel_hi:[1,0,1]
	v_mov_b32_e32 v42, v47
	v_pk_fma_f32 v[52:53], v[38:39], v[44:45], v[52:53] op_sel_hi:[1,1,0] neg_lo:[0,0,1] neg_hi:[0,0,1]
	v_pk_fma_f32 v[44:45], v[30:31], v[46:47], v[60:61] op_sel_hi:[1,1,0] neg_lo:[0,0,1] neg_hi:[0,0,1]
	v_pk_fma_f32 v[40:41], v[38:39], v[40:41], v[54:55] op_sel_hi:[1,1,0]
	v_pk_fma_f32 v[42:43], v[30:31], v[42:43], v[62:63] op_sel_hi:[1,1,0]
	v_sub_f32_e32 v26, v56, v58
	v_sub_f32_e32 v28, v48, v50
	v_mov_b32_e32 v30, v44
	v_mov_b32_e32 v38, v52
	v_mov_b32_e32 v31, v42
	v_mov_b32_e32 v39, v40
.LBB0_361:
	v_cvt_pk_bf16_f32 v40, v28, v29
	v_cvt_pk_bf16_f32 v41, v38, v39
	v_cvt_pk_bf16_f32 v42, v26, v27
	v_mov_b64_e32 v[26:27], s[40:41]
	v_mad_i64_i32 v[26:27], s[0:1], v34, s95, v[26:27]
	v_lshl_add_u64 v[28:29], v[120:121], 1, v[26:27]
	v_mov_b32_e32 v37, v36
	v_cvt_pk_bf16_f32 v43, v30, v31
	global_store_dwordx4 v[28:29], v[40:43], off
	v_mov_b32_e32 v28, v36
	v_mov_b32_e32 v29, v36
	v_pk_mul_f32 v[22:23], v[22:23], v[28:29]
	v_pk_mul_f32 v[20:21], v[20:21], v[36:37]
	v_pk_mul_f32 v[18:19], v[18:19], v[28:29]
	s_and_b64 vcc, exec, s[8:9]
	v_pk_mul_f32 v[16:17], v[16:17], v[36:37]
	s_cbranch_vccnz .LBB0_363
	s_add_i32 s0, s53, 0xffffff80
	s_lshr_b32 s0, s0, 1
	v_or_b32_e32 v136, s0, v162
	v_lshlrev_b64 v[28:29], 2, v[136:137]
	v_lshl_add_u64 v[30:31], v[32:33], 0, v[28:29]
	v_lshl_add_u64 v[24:25], v[24:25], 0, v[28:29]
	v_mov_b64_e32 v[28:29], v[244:245]
	v_mov_b64_e32 v[30:31], v[246:247]
	v_mov_b64_e32 v[32:33], v[248:249]
	v_mov_b64_e32 v[34:35], v[250:251]
	v_pk_mul_f32 v[24:25], v[20:21], v[28:29]
	v_pk_mul_f32 v[36:37], v[20:21], v[32:33] op_sel:[1,0] op_sel_hi:[0,0]
	v_pk_mul_f32 v[44:45], v[16:17], v[34:35] op_sel:[1,0] op_sel_hi:[0,0]
	v_mov_b32_e32 v32, v29
	v_mul_f32_e32 v38, v23, v33
	v_mul_f32_e32 v40, v23, v29
	v_pk_mul_f32 v[42:43], v[16:17], v[30:31]
	v_mov_b32_e32 v34, v31
	v_mul_f32_e32 v46, v19, v35
	v_mul_f32_e32 v48, v19, v31
	v_pk_fma_f32 v[20:21], v[20:21], v[28:29], v[36:37] op_sel_hi:[1,0,1]
	v_mov_b32_e32 v28, v33
	v_pk_fma_f32 v[16:17], v[16:17], v[30:31], v[44:45] op_sel_hi:[1,0,1]
	v_mov_b32_e32 v30, v35
	v_pk_fma_f32 v[38:39], v[22:23], v[32:33], v[38:39] op_sel_hi:[1,1,0] neg_lo:[0,0,1] neg_hi:[0,0,1]
	v_pk_fma_f32 v[32:33], v[18:19], v[34:35], v[46:47] op_sel_hi:[1,1,0] neg_lo:[0,0,1] neg_hi:[0,0,1]
	v_pk_fma_f32 v[28:29], v[22:23], v[28:29], v[40:41] op_sel_hi:[1,1,0]
	v_pk_fma_f32 v[30:31], v[18:19], v[30:31], v[48:49] op_sel_hi:[1,1,0]
	v_sub_f32_e32 v16, v42, v44
	v_sub_f32_e32 v20, v24, v36
	v_mov_b32_e32 v18, v32
	v_mov_b32_e32 v22, v38
	v_mov_b32_e32 v19, v30
	v_mov_b32_e32 v23, v28
.LBB0_363:
	v_cvt_pk_bf16_f32 v20, v20, v21
	v_cvt_pk_bf16_f32 v21, v22, v23
	v_cvt_pk_bf16_f32 v22, v16, v17
	v_lshl_add_u64 v[16:17], v[112:113], 1, v[26:27]
	v_cvt_pk_bf16_f32 v23, v18, v19
	global_store_dwordx4 v[16:17], v[20:23], off offset:256
	s_nop 0
	v_add_u32_e32 v18, 0xb0, v148
	v_ashrrev_i32_e32 v19, 31, v18
	s_and_b64 vcc, exec, s[6:7]
	v_mov_b32_e32 v16, v167
	v_fmamk_f32 v16, v16, 0x3b000000, v166
	v_mul_f32_e32 v17, 0x4b800000, v16
	v_cmp_gt_f32_e64 s[0:1], s94, v16
	s_nop 1
	v_cndmask_b32_e64 v16, v16, v17, s[0:1]
	v_rsq_f32_e32 v20, v16
	v_lshlrev_b64 v[16:17], 5, v[18:19]
	v_lshlrev_b64 v[24:25], 2, v[16:17]
	v_lshl_add_u64 v[16:17], s[12:13], 0, v[24:25]
	v_mul_f32_e32 v19, 0x45800000, v20
	v_cndmask_b32_e64 v19, v20, v19, s[0:1]
	v_mul_f32_e32 v20, 0x3dd53b94, v19
	v_pk_mul_f32 v[22:23], v[14:15], v[20:21] op_sel_hi:[1,0]
	v_pk_mul_f32 v[12:13], v[12:13], v[20:21] op_sel_hi:[1,0]
	v_pk_mul_f32 v[14:15], v[10:11], v[20:21] op_sel_hi:[1,0]
	v_pk_mul_f32 v[10:11], v[8:9], v[20:21] op_sel_hi:[1,0]
	v_lshl_add_u64 v[8:9], s[14:15], 0, v[24:25]
	s_cbranch_vccnz .LBB0_365
	s_addk_i32 s51, 0xff80
	s_lshr_b32 s0, s51, 1
	v_or_b32_e32 v136, s0, v162
	v_lshlrev_b64 v[24:25], 2, v[136:137]
	v_lshl_add_u64 v[26:27], v[16:17], 0, v[24:25]
	v_lshl_add_u64 v[28:29], v[8:9], 0, v[24:25]
	s_waitcnt vmcnt(13)
	v_mov_b64_e32 v[24:25], v[190:191]
	v_mov_b64_e32 v[26:27], v[192:193]
	v_mov_b64_e32 v[28:29], v[194:195]
	v_mov_b64_e32 v[30:31], v[196:197]
	v_pk_mul_f32 v[32:33], v[12:13], v[24:25]
	v_pk_mul_f32 v[34:35], v[12:13], v[28:29] op_sel:[1,0] op_sel_hi:[0,0]
	v_pk_mul_f32 v[42:43], v[10:11], v[30:31] op_sel:[1,0] op_sel_hi:[0,0]
	v_mov_b32_e32 v28, v25
	v_mul_f32_e32 v36, v23, v29
	v_mul_f32_e32 v38, v23, v25
	v_pk_mul_f32 v[40:41], v[10:11], v[26:27]
	v_mov_b32_e32 v30, v27
	v_mul_f32_e32 v44, v15, v31
	v_mul_f32_e32 v46, v15, v27
	v_pk_fma_f32 v[12:13], v[12:13], v[24:25], v[34:35] op_sel_hi:[1,0,1]
	v_mov_b32_e32 v24, v29
	v_pk_fma_f32 v[10:11], v[10:11], v[26:27], v[42:43] op_sel_hi:[1,0,1]
	v_mov_b32_e32 v26, v31
	v_pk_fma_f32 v[36:37], v[22:23], v[28:29], v[36:37] op_sel_hi:[1,1,0] neg_lo:[0,0,1] neg_hi:[0,0,1]
	v_pk_fma_f32 v[28:29], v[14:15], v[30:31], v[44:45] op_sel_hi:[1,1,0] neg_lo:[0,0,1] neg_hi:[0,0,1]
	v_pk_fma_f32 v[24:25], v[22:23], v[24:25], v[38:39] op_sel_hi:[1,1,0]
	v_pk_fma_f32 v[26:27], v[14:15], v[26:27], v[46:47] op_sel_hi:[1,1,0]
	v_sub_f32_e32 v10, v40, v42
	v_sub_f32_e32 v12, v32, v34
	v_mov_b32_e32 v14, v28
	v_mov_b32_e32 v22, v36
	v_mov_b32_e32 v15, v26
	v_mov_b32_e32 v23, v24
.LBB0_365:
	v_cvt_pk_bf16_f32 v24, v12, v13
	v_cvt_pk_bf16_f32 v25, v22, v23
	v_cvt_pk_bf16_f32 v26, v10, v11
	v_mov_b64_e32 v[10:11], s[40:41]
	v_mad_i64_i32 v[10:11], s[0:1], v18, s95, v[10:11]
	v_lshl_add_u64 v[12:13], v[120:121], 1, v[10:11]
	v_mov_b32_e32 v21, v20
	v_cvt_pk_bf16_f32 v27, v14, v15
	global_store_dwordx4 v[12:13], v[24:27], off
	v_mov_b32_e32 v12, v20
	v_mov_b32_e32 v13, v20
	v_pk_mul_f32 v[6:7], v[6:7], v[12:13]
	v_pk_mul_f32 v[4:5], v[4:5], v[20:21]
	v_pk_mul_f32 v[2:3], v[2:3], v[12:13]
	s_and_b64 vcc, exec, s[8:9]
	v_pk_mul_f32 v[0:1], v[0:1], v[20:21]
	s_cbranch_vccnz .LBB0_367
	s_addk_i32 s53, 0xff80
	s_lshr_b32 s0, s53, 1
	v_or_b32_e32 v136, s0, v162
	v_lshlrev_b64 v[12:13], 2, v[136:137]
	v_lshl_add_u64 v[14:15], v[16:17], 0, v[12:13]
	v_lshl_add_u64 v[8:9], v[8:9], 0, v[12:13]
	s_waitcnt vmcnt(13)
	v_mov_b64_e32 v[12:13], v[190:191]
	v_mov_b64_e32 v[14:15], v[192:193]
	v_mov_b64_e32 v[16:17], v[194:195]
	v_mov_b64_e32 v[18:19], v[196:197]
	v_pk_mul_f32 v[8:9], v[4:5], v[12:13]
	v_pk_mul_f32 v[20:21], v[4:5], v[16:17] op_sel:[1,0] op_sel_hi:[0,0]
	v_pk_mul_f32 v[28:29], v[0:1], v[18:19] op_sel:[1,0] op_sel_hi:[0,0]
	v_mov_b32_e32 v16, v13
	v_mul_f32_e32 v22, v7, v17
	v_mul_f32_e32 v24, v7, v13
	v_pk_mul_f32 v[26:27], v[0:1], v[14:15]
	v_mov_b32_e32 v18, v15
	v_mul_f32_e32 v30, v3, v19
	v_mul_f32_e32 v32, v3, v15
	v_pk_fma_f32 v[4:5], v[4:5], v[12:13], v[20:21] op_sel_hi:[1,0,1]
	v_mov_b32_e32 v12, v17
	v_pk_fma_f32 v[0:1], v[0:1], v[14:15], v[28:29] op_sel_hi:[1,0,1]
	v_mov_b32_e32 v14, v19
	v_pk_fma_f32 v[22:23], v[6:7], v[16:17], v[22:23] op_sel_hi:[1,1,0] neg_lo:[0,0,1] neg_hi:[0,0,1]
	v_pk_fma_f32 v[16:17], v[2:3], v[18:19], v[30:31] op_sel_hi:[1,1,0] neg_lo:[0,0,1] neg_hi:[0,0,1]
	v_pk_fma_f32 v[12:13], v[6:7], v[12:13], v[24:25] op_sel_hi:[1,1,0]
	v_pk_fma_f32 v[14:15], v[2:3], v[14:15], v[32:33] op_sel_hi:[1,1,0]
	v_sub_f32_e32 v0, v26, v28
	v_sub_f32_e32 v4, v8, v20
	v_mov_b32_e32 v2, v16
	v_mov_b32_e32 v6, v22
	v_mov_b32_e32 v3, v14
	v_mov_b32_e32 v7, v12

.LBB0_389:
	v_lshl_add_u32 v144, s54, 8, v150
	v_ashrrev_i32_e32 v145, 31, v144
	v_lshl_add_u64 v[142:143], v[144:145], 2, s[8:9]
	global_load_dword v170, v[142:143], off
	global_load_dword v171, v[142:143], off offset:64
	global_load_dword v172, v[142:143], off offset:128
	global_load_dword v173, v[142:143], off offset:192
	global_load_dword v174, v[142:143], off offset:512
	global_load_dword v175, v[142:143], off offset:576
	global_load_dword v176, v[142:143], off offset:640
	global_load_dword v177, v[142:143], off offset:704
	v_lshlrev_b64 v[160:161], 11, v[144:145]
	s_mul_i32 s10, s97, 0xc0
	s_lshl_b32 s54, s97, 7
	v_mov_b64_e32 v[146:147], s[42:43]
	s_ashr_i32 s11, s10, 31
	s_ashr_i32 s55, s54, 31
	v_mad_i64_i32 v[148:149], s[60:61], v144, s96, v[146:147]
	s_lshl_b64 s[70:71], s[10:11], 1
	s_lshl_b64 s[54:55], s[54:55], 1
	v_lshl_add_u64 v[148:149], v[148:149], 0, s[70:71]
	v_lshl_add_u64 v[160:161], s[38:39], 0, v[160:161]
	v_lshl_add_u64 v[164:165], v[148:149], 0, v[136:137]
	v_lshl_add_u64 v[148:149], v[160:161], 0, s[54:55]
	v_lshl_add_u64 v[160:161], v[148:149], 0, v[136:137]
	v_or_b32_e32 v158, 16, v144
	v_ashrrev_i32_e32 v159, 31, v158
	v_lshl_add_u64 v[162:163], v[158:159], 2, s[8:9]
	s_waitcnt vmcnt(0)
	v_mov_b32_e32 v157, v170
	v_fmamk_f32 v145, v157, 0x3b800000, v156
	v_mul_f32_e32 v157, 0x4b800000, v145
	v_cmp_gt_f32_e32 vcc, s95, v145
	s_nop 1
	v_cndmask_b32_e32 v145, v145, v157, vcc
	v_rsq_f32_e32 v145, v145
	s_nop 0
	v_mul_f32_e32 v148, 0x45800000, v145
	v_cndmask_b32_e32 v166, v145, v148, vcc
	v_pk_mul_f32 v[114:115], v[114:115], v[166:167] op_sel_hi:[1,0]
	v_pk_mul_f32 v[148:149], v[112:113], v[166:167] op_sel_hi:[1,0]
	v_pk_mul_f32 v[112:113], v[118:119], v[166:167] op_sel_hi:[1,0]
	v_pk_mul_f32 v[116:117], v[116:117], v[166:167] op_sel_hi:[1,0]
	v_pk_mul_f32 v[168:169], v[120:121], v[166:167] op_sel_hi:[1,0]
	v_cvt_pk_bf16_f32 v118, v148, v149
	v_cvt_pk_bf16_f32 v119, v114, v115
	v_cvt_pk_bf16_f32 v120, v116, v117
	v_cvt_pk_bf16_f32 v121, v112, v113
	v_pk_mul_f32 v[122:123], v[122:123], v[166:167] op_sel_hi:[1,0]
	v_pk_mul_f32 v[126:127], v[126:127], v[166:167] op_sel_hi:[1,0]
	v_pk_mul_f32 v[124:125], v[124:125], v[166:167] op_sel_hi:[1,0]
	global_store_dwordx4 v[164:165], v[118:121], off
	s_nop 1
	v_cvt_pk_bf16_f32 v118, v168, v169
	v_cvt_pk_bf16_f32 v119, v122, v123
	v_cvt_pk_bf16_f32 v120, v124, v125
	v_cvt_pk_bf16_f32 v121, v126, v127
	global_store_dwordx4 v[160:161], v[118:121], off
	s_nop 0
	v_lshlrev_b64 v[122:123], 11, v[158:159]
	v_mad_i64_i32 v[118:119], s[10:11], v158, s96, v[146:147]
	v_lshl_add_u64 v[118:119], v[118:119], 0, s[70:71]
	v_lshl_add_u64 v[126:127], v[118:119], 0, v[136:137]
	v_or_b32_e32 v120, 32, v144
	v_ashrrev_i32_e32 v121, 31, v120
	v_lshl_add_u64 v[124:125], v[120:121], 2, s[8:9]
	v_mov_b32_e32 v145, v171
	v_fmamk_f32 v118, v145, 0x3b800000, v156
	v_mul_f32_e32 v119, 0x4b800000, v118
	v_cmp_gt_f32_e32 vcc, s95, v118
	s_nop 1
	v_cndmask_b32_e32 v118, v118, v119, vcc
	v_rsq_f32_e32 v145, v118
	v_lshl_add_u64 v[118:119], s[38:39], 0, v[122:123]
	v_lshl_add_u64 v[118:119], v[118:119], 0, s[54:55]
	v_lshl_add_u64 v[122:123], v[118:119], 0, v[136:137]
	v_mul_f32_e32 v118, 0x45800000, v145
	v_cndmask_b32_e32 v158, v145, v118, vcc
	v_pk_mul_f32 v[98:99], v[98:99], v[158:159] op_sel_hi:[1,0]
	v_pk_mul_f32 v[118:119], v[96:97], v[158:159] op_sel_hi:[1,0]
	v_pk_mul_f32 v[96:97], v[102:103], v[158:159] op_sel_hi:[1,0]
	v_pk_mul_f32 v[100:101], v[100:101], v[158:159] op_sel_hi:[1,0]
	v_pk_mul_f32 v[160:161], v[104:105], v[158:159] op_sel_hi:[1,0]
	v_cvt_pk_bf16_f32 v102, v118, v119
	v_cvt_pk_bf16_f32 v103, v98, v99
	v_cvt_pk_bf16_f32 v104, v100, v101
	v_cvt_pk_bf16_f32 v105, v96, v97
	v_pk_mul_f32 v[106:107], v[106:107], v[158:159] op_sel_hi:[1,0]
	v_pk_mul_f32 v[110:111], v[110:111], v[158:159] op_sel_hi:[1,0]
	v_pk_mul_f32 v[108:109], v[108:109], v[158:159] op_sel_hi:[1,0]
	global_store_dwordx4 v[126:127], v[102:105], off
	s_nop 1
	v_cvt_pk_bf16_f32 v102, v160, v161
	v_cvt_pk_bf16_f32 v103, v106, v107
	v_cvt_pk_bf16_f32 v104, v108, v109
	v_cvt_pk_bf16_f32 v105, v110, v111
	global_store_dwordx4 v[122:123], v[102:105], off
	s_nop 0
	v_lshlrev_b64 v[106:107], 11, v[120:121]
	v_mad_i64_i32 v[102:103], s[10:11], v120, s96, v[146:147]
	v_lshl_add_u64 v[102:103], v[102:103], 0, s[70:71]
	v_lshl_add_u64 v[110:111], v[102:103], 0, v[136:137]
	v_or_b32_e32 v104, 48, v144
	v_ashrrev_i32_e32 v105, 31, v104
	v_lshl_add_u64 v[108:109], v[104:105], 2, s[8:9]
	v_mov_b32_e32 v122, v172
	v_fmamk_f32 v102, v122, 0x3b800000, v156
	v_mul_f32_e32 v103, 0x4b800000, v102
	v_cmp_gt_f32_e32 vcc, s95, v102
	s_nop 1
	v_cndmask_b32_e32 v102, v102, v103, vcc
	v_rsq_f32_e32 v120, v102
	v_lshl_add_u64 v[102:103], s[38:39], 0, v[106:107]
	v_lshl_add_u64 v[102:103], v[102:103], 0, s[54:55]
	v_lshl_add_u64 v[106:107], v[102:103], 0, v[136:137]
	v_mul_f32_e32 v102, 0x45800000, v120
	v_cndmask_b32_e32 v120, v120, v102, vcc
	v_pk_mul_f32 v[82:83], v[82:83], v[120:121] op_sel_hi:[1,0]
	v_pk_mul_f32 v[102:103], v[80:81], v[120:121] op_sel_hi:[1,0]
	v_pk_mul_f32 v[80:81], v[86:87], v[120:121] op_sel_hi:[1,0]
	v_pk_mul_f32 v[84:85], v[84:85], v[120:121] op_sel_hi:[1,0]
	v_pk_mul_f32 v[122:123], v[88:89], v[120:121] op_sel_hi:[1,0]
	v_cvt_pk_bf16_f32 v86, v102, v103
	v_cvt_pk_bf16_f32 v87, v82, v83
	v_cvt_pk_bf16_f32 v88, v84, v85
	v_cvt_pk_bf16_f32 v89, v80, v81
	v_pk_mul_f32 v[90:91], v[90:91], v[120:121] op_sel_hi:[1,0]
	v_pk_mul_f32 v[94:95], v[94:95], v[120:121] op_sel_hi:[1,0]
	v_pk_mul_f32 v[92:93], v[92:93], v[120:121] op_sel_hi:[1,0]
	global_store_dwordx4 v[110:111], v[86:89], off
	s_nop 1
	v_cvt_pk_bf16_f32 v86, v122, v123
	v_cvt_pk_bf16_f32 v87, v90, v91
	v_cvt_pk_bf16_f32 v88, v92, v93
	v_cvt_pk_bf16_f32 v89, v94, v95
	global_store_dwordx4 v[106:107], v[86:89], off
	s_nop 0
	s_nop 0
	v_mad_i64_i32 v[86:87], s[10:11], v104, s96, v[146:147]
	v_lshl_add_u64 v[86:87], v[86:87], 0, s[70:71]
	v_lshl_add_u64 v[90:91], v[86:87], 0, v[136:137]
	v_lshlrev_b64 v[88:89], 11, v[104:105]
	v_mov_b32_e32 v92, v173
	v_fmamk_f32 v86, v92, 0x3b800000, v156
	v_mul_f32_e32 v87, 0x4b800000, v86
	v_cmp_gt_f32_e32 vcc, s95, v86
	s_nop 1
	v_cndmask_b32_e32 v86, v86, v87, vcc
	v_rsq_f32_e32 v92, v86
	v_lshl_add_u64 v[86:87], s[38:39], 0, v[88:89]
	v_lshl_add_u64 v[86:87], v[86:87], 0, s[54:55]
	v_lshl_add_u64 v[88:89], v[86:87], 0, v[136:137]
	v_mul_f32_e32 v86, 0x45800000, v92
	v_cndmask_b32_e32 v92, v92, v86, vcc
	v_pk_mul_f32 v[66:67], v[66:67], v[92:93] op_sel_hi:[1,0]
	v_pk_mul_f32 v[86:87], v[64:65], v[92:93] op_sel_hi:[1,0]
	v_pk_mul_f32 v[64:65], v[70:71], v[92:93] op_sel_hi:[1,0]
	v_pk_mul_f32 v[68:69], v[68:69], v[92:93] op_sel_hi:[1,0]
	v_pk_mul_f32 v[94:95], v[72:73], v[92:93] op_sel_hi:[1,0]
	v_cvt_pk_bf16_f32 v70, v86, v87
	v_cvt_pk_bf16_f32 v71, v66, v67
	v_cvt_pk_bf16_f32 v72, v68, v69
	v_cvt_pk_bf16_f32 v73, v64, v65
	v_pk_mul_f32 v[74:75], v[74:75], v[92:93] op_sel_hi:[1,0]
	v_pk_mul_f32 v[78:79], v[78:79], v[92:93] op_sel_hi:[1,0]
	v_pk_mul_f32 v[76:77], v[76:77], v[92:93] op_sel_hi:[1,0]
	global_store_dwordx4 v[90:91], v[70:73], off
	s_nop 1
	v_cvt_pk_bf16_f32 v70, v94, v95
	v_cvt_pk_bf16_f32 v71, v74, v75
	v_cvt_pk_bf16_f32 v72, v76, v77
	v_cvt_pk_bf16_f32 v73, v78, v79
	global_store_dwordx4 v[88:89], v[70:73], off
	s_nop 0
	v_mov_b32_e32 v74, v174
	v_fmamk_f32 v74, v74, 0x3b800000, v156
	v_mul_f32_e32 v75, 0x4b800000, v74
	v_cmp_gt_f32_e32 vcc, s95, v74
	v_add_u32_e32 v70, 0x80, v144
	v_ashrrev_i32_e32 v71, 31, v70
	v_cndmask_b32_e32 v74, v74, v75, vcc
	v_rsq_f32_e32 v76, v74
	v_mad_i64_i32 v[72:73], s[10:11], v70, s96, v[146:147]
	v_lshlrev_b64 v[70:71], 11, v[70:71]
	v_lshl_add_u64 v[70:71], s[38:39], 0, v[70:71]
	v_lshl_add_u64 v[70:71], v[70:71], 0, s[54:55]
	v_lshl_add_u64 v[74:75], v[70:71], 0, v[136:137]
	v_mul_f32_e32 v70, 0x45800000, v76
	v_lshl_add_u64 v[72:73], v[72:73], 0, s[70:71]
	v_cndmask_b32_e32 v76, v76, v70, vcc
	v_lshl_add_u64 v[72:73], v[72:73], 0, v[136:137]
	v_pk_mul_f32 v[50:51], v[50:51], v[76:77] op_sel_hi:[1,0]
	v_pk_mul_f32 v[70:71], v[48:49], v[76:77] op_sel_hi:[1,0]
	v_pk_mul_f32 v[48:49], v[54:55], v[76:77] op_sel_hi:[1,0]
	v_pk_mul_f32 v[52:53], v[52:53], v[76:77] op_sel_hi:[1,0]
	v_pk_mul_f32 v[78:79], v[56:57], v[76:77] op_sel_hi:[1,0]
	v_cvt_pk_bf16_f32 v54, v70, v71
	v_cvt_pk_bf16_f32 v55, v50, v51
	v_cvt_pk_bf16_f32 v56, v52, v53
	v_cvt_pk_bf16_f32 v57, v48, v49
	v_pk_mul_f32 v[58:59], v[58:59], v[76:77] op_sel_hi:[1,0]
	v_pk_mul_f32 v[62:63], v[62:63], v[76:77] op_sel_hi:[1,0]
	v_pk_mul_f32 v[60:61], v[60:61], v[76:77] op_sel_hi:[1,0]
	global_store_dwordx4 v[72:73], v[54:57], off
	s_nop 1
	v_cvt_pk_bf16_f32 v54, v78, v79
	v_cvt_pk_bf16_f32 v55, v58, v59
	v_cvt_pk_bf16_f32 v56, v60, v61
	v_cvt_pk_bf16_f32 v57, v62, v63
	global_store_dwordx4 v[74:75], v[54:57], off
	s_nop 0
	v_mov_b32_e32 v58, v175
	v_fmamk_f32 v58, v58, 0x3b800000, v156
	v_mul_f32_e32 v59, 0x4b800000, v58
	v_cmp_gt_f32_e32 vcc, s95, v58
	v_add_u32_e32 v54, 0x90, v144
	v_ashrrev_i32_e32 v55, 31, v54
	v_cndmask_b32_e32 v58, v58, v59, vcc
	v_rsq_f32_e32 v60, v58
	v_mad_i64_i32 v[56:57], s[10:11], v54, s96, v[146:147]
	v_lshlrev_b64 v[54:55], 11, v[54:55]
	v_lshl_add_u64 v[54:55], s[38:39], 0, v[54:55]
	v_lshl_add_u64 v[54:55], v[54:55], 0, s[54:55]
	v_lshl_add_u64 v[58:59], v[54:55], 0, v[136:137]
	v_mul_f32_e32 v54, 0x45800000, v60
	v_lshl_add_u64 v[56:57], v[56:57], 0, s[70:71]
	v_cndmask_b32_e32 v60, v60, v54, vcc
	v_lshl_add_u64 v[56:57], v[56:57], 0, v[136:137]
	v_pk_mul_f32 v[34:35], v[34:35], v[60:61] op_sel_hi:[1,0]
	v_pk_mul_f32 v[54:55], v[32:33], v[60:61] op_sel_hi:[1,0]
	v_pk_mul_f32 v[32:33], v[38:39], v[60:61] op_sel_hi:[1,0]
	v_pk_mul_f32 v[36:37], v[36:37], v[60:61] op_sel_hi:[1,0]
	v_pk_mul_f32 v[62:63], v[40:41], v[60:61] op_sel_hi:[1,0]
	v_cvt_pk_bf16_f32 v38, v54, v55
	v_cvt_pk_bf16_f32 v39, v34, v35
	v_cvt_pk_bf16_f32 v40, v36, v37
	v_cvt_pk_bf16_f32 v41, v32, v33
	v_pk_mul_f32 v[42:43], v[42:43], v[60:61] op_sel_hi:[1,0]
	v_pk_mul_f32 v[46:47], v[46:47], v[60:61] op_sel_hi:[1,0]
	v_pk_mul_f32 v[44:45], v[44:45], v[60:61] op_sel_hi:[1,0]
	global_store_dwordx4 v[56:57], v[38:41], off
	v_xor_b32_e32 v56, 2, v155
	v_xor_b32_e32 v57, 4, v155
	v_cvt_pk_bf16_f32 v38, v62, v63
	v_cvt_pk_bf16_f32 v39, v42, v43
	v_cvt_pk_bf16_f32 v40, v44, v45
	v_cvt_pk_bf16_f32 v41, v46, v47
	global_store_dwordx4 v[58:59], v[38:41], off
	s_nop 0
	v_xor_b32_e32 v47, 1, v155
	v_and_b32_e32 v38, 64, v155
	v_xor_b32_e32 v39, 16, v155
	v_add_u32_e32 v59, 64, v38
	v_xor_b32_e32 v41, 32, v155
	v_cmp_lt_i32_e32 vcc, v39, v59
	v_xor_b32_e32 v58, 8, v155
	v_add_u32_e32 v38, 0xa0, v144
	v_cndmask_b32_e32 v60, v155, v39, vcc
	v_cmp_lt_i32_e32 vcc, v41, v59
	v_ashrrev_i32_e32 v39, 31, v38
	v_mad_i64_i32 v[42:43], s[10:11], v38, s96, v[146:147]
	v_cndmask_b32_e32 v61, v155, v41, vcc
	v_cmp_lt_i32_e32 vcc, v47, v59
	v_lshlrev_b64 v[38:39], 11, v[38:39]
	v_lshl_add_u64 v[38:39], s[38:39], 0, v[38:39]
	v_cndmask_b32_e32 v47, v155, v47, vcc
	v_cmp_lt_i32_e32 vcc, v56, v59
	v_lshl_add_u64 v[42:43], v[42:43], 0, s[70:71]
	v_lshl_add_u64 v[38:39], v[38:39], 0, s[54:55]
	v_cndmask_b32_e32 v62, v155, v56, vcc
	v_cmp_lt_i32_e32 vcc, v57, v59
	v_mul_f32_e32 v56, v149, v149
	v_fmac_f32_e32 v56, v148, v148
	v_cndmask_b32_e32 v63, v155, v57, vcc
	v_cmp_lt_i32_e32 vcc, v58, v59
	v_mul_f32_e32 v57, v115, v115
	v_fmac_f32_e32 v57, v114, v114
	v_cndmask_b32_e32 v72, v155, v58, vcc
	v_mul_f32_e32 v58, v117, v117
	v_mul_f32_e32 v59, v113, v113
	v_fmac_f32_e32 v58, v116, v116
	v_add_f32_e32 v56, v56, v57
	v_fmac_f32_e32 v59, v112, v112
	v_add_f32_e32 v56, v58, v56
	v_add_f32_e32 v73, v59, v56
	v_mul_f32_e32 v56, v119, v119
	v_mul_f32_e32 v57, v99, v99
	v_fmac_f32_e32 v56, v118, v118
	v_fmac_f32_e32 v57, v98, v98
	v_add_f32_e32 v56, v56, v57
	v_mul_f32_e32 v58, v101, v101
	v_mul_f32_e32 v59, v97, v97
	v_fmac_f32_e32 v58, v100, v100
	v_fmac_f32_e32 v59, v96, v96
	v_add_f32_e32 v56, v58, v56
	v_add_f32_e32 v75, v59, v56
	v_lshl_add_u64 v[42:43], v[42:43], 0, v[136:137]
	v_lshl_add_u64 v[38:39], v[38:39], 0, v[136:137]
	v_lshlrev_b32_e32 v60, 2, v60
	ds_bpermute_b32 v74, v60, v73
	ds_bpermute_b32 v76, v60, v75
	v_lshlrev_b32_e32 v61, 2, v61
	v_add_u32_e32 v40, 0xb0, v144
	v_ashrrev_i32_e32 v41, 31, v40
	v_mad_i64_i32 v[44:45], s[10:11], v40, s96, v[146:147]
	v_mul_f32_e32 v33, v33, v33
	v_fmac_f32_e32 v33, v32, v32
	v_lshl_add_u64 v[44:45], v[44:45], 0, s[70:71]
	v_mov_b32_e32 v46, v176
	v_fmamk_f32 v46, v46, 0x3b800000, v156
	v_mul_f32_e32 v57, 0x4b800000, v46
	v_cmp_gt_f32_e32 vcc, s95, v46
	s_nop 1
	v_cndmask_b32_e32 v46, v46, v57, vcc
	v_rsq_f32_e32 v46, v46
	s_nop 0
	v_mul_f32_e32 v56, 0x45800000, v46
	v_cndmask_b32_e32 v46, v46, v56, vcc
	v_pk_mul_f32 v[56:57], v[18:19], v[46:47] op_sel_hi:[1,0]
	v_pk_mul_f32 v[58:59], v[16:17], v[46:47] op_sel_hi:[1,0]
	v_pk_mul_f32 v[22:23], v[22:23], v[46:47] op_sel_hi:[1,0]
	v_pk_mul_f32 v[20:21], v[20:21], v[46:47] op_sel_hi:[1,0]
	v_cvt_pk_bf16_f32 v16, v58, v59
	v_cvt_pk_bf16_f32 v17, v56, v57
	v_pk_mul_f32 v[26:27], v[26:27], v[46:47] op_sel_hi:[1,0]
	v_cvt_pk_bf16_f32 v18, v20, v21
	v_cvt_pk_bf16_f32 v19, v22, v23
	v_pk_mul_f32 v[24:25], v[24:25], v[46:47] op_sel_hi:[1,0]
	v_pk_mul_f32 v[30:31], v[30:31], v[46:47] op_sel_hi:[1,0]
	v_pk_mul_f32 v[28:29], v[28:29], v[46:47] op_sel_hi:[1,0]
	global_store_dwordx4 v[42:43], v[16:19], off
	v_mul_f32_e32 v23, v23, v23
	v_fmac_f32_e32 v23, v22, v22
	v_cvt_pk_bf16_f32 v16, v24, v25
	v_cvt_pk_bf16_f32 v17, v26, v27
	v_cvt_pk_bf16_f32 v18, v28, v29
	v_cvt_pk_bf16_f32 v19, v30, v31
	global_store_dwordx4 v[38:39], v[16:19], off
	s_nop 0
	s_waitcnt lgkmcnt(1)
	v_add_f32_e32 v26, v73, v74
	s_waitcnt lgkmcnt(0)
	v_add_f32_e32 v28, v75, v76
	ds_bpermute_b32 v27, v61, v26
	ds_bpermute_b32 v29, v61, v28
	v_mul_f32_e32 v38, v85, v85
	v_mul_f32_e32 v39, v81, v81
	v_fmac_f32_e32 v38, v84, v84
	s_waitcnt lgkmcnt(1)
	v_add_f32_e32 v26, v26, v27
	s_waitcnt lgkmcnt(0)
	v_add_f32_e32 v27, v28, v29
	v_mul_f32_e32 v28, v103, v103
	v_mul_f32_e32 v29, v83, v83
	v_fmac_f32_e32 v28, v102, v102
	v_fmac_f32_e32 v29, v82, v82
	v_add_f32_e32 v28, v28, v29
	v_fmac_f32_e32 v39, v80, v80
	v_add_f32_e32 v28, v38, v28
	v_add_f32_e32 v28, v39, v28
	v_mul_f32_e32 v38, v87, v87
	v_mul_f32_e32 v39, v67, v67
	v_lshlrev_b64 v[16:17], 11, v[40:41]
	v_mul_f32_e32 v40, v69, v69
	v_fmac_f32_e32 v38, v86, v86
	v_fmac_f32_e32 v39, v66, v66
	v_mul_f32_e32 v41, v65, v65
	v_fmac_f32_e32 v40, v68, v68
	v_add_f32_e32 v38, v38, v39
	v_fmac_f32_e32 v41, v64, v64
	v_add_f32_e32 v38, v40, v38
	v_add_f32_e32 v38, v41, v38
	ds_bpermute_b32 v29, v60, v28
	ds_bpermute_b32 v39, v60, v38
	v_max3_f32 v26, v26, 0, v27
	v_mul_f32_e32 v32, v59, v59
	v_mul_f32_e32 v21, v21, v21
	s_waitcnt lgkmcnt(1)
	v_add_f32_e32 v28, v28, v29
	s_waitcnt lgkmcnt(0)
	v_add_f32_e32 v38, v38, v39
	ds_bpermute_b32 v29, v61, v28
	ds_bpermute_b32 v39, v61, v38
	v_fmac_f32_e32 v32, v58, v58
	v_fmac_f32_e32 v21, v20, v20
	v_mul_f32_e32 v40, v71, v71
	s_waitcnt lgkmcnt(1)
	v_add_f32_e32 v27, v28, v29
	s_waitcnt lgkmcnt(0)
	v_add_f32_e32 v28, v38, v39
	v_max3_f32 v26, v26, v27, v28
	v_mul_f32_e32 v28, v55, v55
	v_mul_f32_e32 v29, v35, v35
	v_mul_f32_e32 v35, v37, v37
	v_fmac_f32_e32 v28, v54, v54
	v_fmac_f32_e32 v29, v34, v34
	v_fmac_f32_e32 v35, v36, v36
	v_add_f32_e32 v28, v28, v29
	v_add_f32_e32 v28, v35, v28
	v_add_f32_e32 v28, v33, v28
	v_mul_f32_e32 v33, v57, v57
	v_fmac_f32_e32 v33, v56, v56
	v_add_f32_e32 v20, v32, v33
	v_add_f32_e32 v20, v21, v20
	v_add_f32_e32 v21, v23, v20
	v_mul_f32_e32 v41, v51, v51
	v_mul_f32_e32 v42, v53, v53
	v_fmac_f32_e32 v40, v70, v70
	v_fmac_f32_e32 v41, v50, v50
	v_mul_f32_e32 v43, v49, v49
	v_fmac_f32_e32 v42, v52, v52
	v_add_f32_e32 v40, v40, v41
	v_fmac_f32_e32 v43, v48, v48
	v_add_f32_e32 v40, v42, v40
	v_add_f32_e32 v40, v43, v40
	ds_bpermute_b32 v41, v60, v40
	ds_bpermute_b32 v29, v60, v28
	ds_bpermute_b32 v23, v60, v21
	v_lshlrev_b32_e32 v25, 2, v47
	v_lshlrev_b32_e32 v30, 2, v62
	s_waitcnt lgkmcnt(2)
	v_add_f32_e32 v40, v40, v41
	s_waitcnt lgkmcnt(1)
	v_add_f32_e32 v28, v28, v29
	ds_bpermute_b32 v41, v61, v40
	ds_bpermute_b32 v29, v61, v28
	v_lshl_add_u64 v[18:19], v[44:45], 0, v[136:137]
	v_lshlrev_b32_e32 v31, 2, v63
	v_mov_b32_e32 v24, v177
	v_fmamk_f32 v22, v24, 0x3b800000, v156
	v_mul_f32_e32 v24, 0x4b800000, v22
	v_cmp_gt_f32_e32 vcc, s95, v22
	s_waitcnt lgkmcnt(1)
	v_add_f32_e32 v27, v40, v41
	v_cndmask_b32_e32 v22, v22, v24, vcc
	v_rsq_f32_e32 v22, v22
	s_nop 0
	v_mul_f32_e32 v20, 0x45800000, v22
	v_cndmask_b32_e32 v20, v22, v20, vcc
	v_pk_mul_f32 v[10:11], v[10:11], v[20:21] op_sel_hi:[1,0]
	v_pk_mul_f32 v[8:9], v[8:9], v[20:21] op_sel_hi:[1,0]
	v_pk_mul_f32 v[12:13], v[12:13], v[20:21] op_sel_hi:[1,0]
	v_mul_f32_e32 v22, v9, v9
	v_mul_f32_e32 v24, v11, v11
	v_pk_mul_f32 v[14:15], v[14:15], v[20:21] op_sel_hi:[1,0]
	v_mul_f32_e32 v32, v13, v13
	v_fmac_f32_e32 v22, v8, v8
	v_fmac_f32_e32 v24, v10, v10
	v_mul_f32_e32 v33, v15, v15
	v_fmac_f32_e32 v32, v12, v12
	v_add_f32_e32 v22, v22, v24
	v_fmac_f32_e32 v33, v14, v14
	v_add_f32_e32 v22, v32, v22
	v_add_f32_e32 v22, v33, v22
	ds_bpermute_b32 v24, v60, v22
	v_add_f32_e32 v21, v21, v23
	ds_bpermute_b32 v23, v61, v21
	s_waitcnt lgkmcnt(1)
	v_add_f32_e32 v24, v22, v24
	ds_bpermute_b32 v32, v61, v24
	v_add_f32_e32 v22, v28, v29
	s_waitcnt lgkmcnt(1)
	v_add_f32_e32 v21, v21, v23
	v_max3_f32 v26, v26, v27, v22
	v_pk_mul_f32 v[22:23], v[2:3], v[20:21] op_sel_hi:[1,0]
	s_waitcnt lgkmcnt(0)
	v_add_f32_e32 v2, v24, v32
	v_max3_f32 v2, v26, v21, v2
	ds_bpermute_b32 v3, v25, v2
	v_pk_mul_f32 v[24:25], v[0:1], v[20:21] op_sel_hi:[1,0]
	v_cvt_pk_bf16_f32 v0, v8, v9
	v_pk_mul_f32 v[6:7], v[6:7], v[20:21] op_sel_hi:[1,0]
	v_pk_mul_f32 v[4:5], v[4:5], v[20:21] op_sel_hi:[1,0]
	s_waitcnt lgkmcnt(0)
	v_max_f32_e32 v1, v3, v3
	v_max_f32_e32 v8, v2, v1
	ds_bpermute_b32 v9, v30, v8
	v_cvt_pk_bf16_f32 v1, v10, v11
	v_cvt_pk_bf16_f32 v2, v12, v13
	v_cvt_pk_bf16_f32 v3, v14, v15
	global_store_dwordx4 v[18:19], v[0:3], off
	s_waitcnt lgkmcnt(0)
	s_nop 0
	v_max_f32_e32 v0, v9, v9
	v_max_f32_e32 v0, v8, v0
	ds_bpermute_b32 v1, v31, v0
	v_cvt_pk_bf16_f32 v2, v24, v25
	v_cvt_pk_bf16_f32 v3, v22, v23
	v_cvt_pk_bf16_f32 v4, v4, v5
	v_cvt_pk_bf16_f32 v5, v6, v7
	s_waitcnt lgkmcnt(0)
	v_max_f32_e32 v1, v1, v1
	v_max_f32_e32 v0, v0, v1
	v_lshlrev_b32_e32 v1, 2, v72
	ds_bpermute_b32 v1, v1, v0
	v_lshl_add_u64 v[6:7], s[38:39], 0, v[16:17]
	v_lshl_add_u64 v[6:7], v[6:7], 0, s[54:55]
	v_lshl_add_u64 v[6:7], v[6:7], 0, v[136:137]
	global_store_dwordx4 v[6:7], v[2:5], off
	s_and_saveexec_b64 s[54:55], s[4:5]
	s_cbranch_execz .LBB0_394
	s_waitcnt lgkmcnt(0)
	v_max_f32_e32 v1, v1, v1
	v_max_f32_e32 v0, v0, v0
	s_mov_b64 s[70:71], exec
	v_max_f32_e32 v0, v0, v1
	s_mov_b32 s10, 0

	.amdhsa_kernel _Z8fwd_mega4Args
		.amdhsa_group_segment_fixed_size 0
		.amdhsa_private_segment_fixed_size 0
		.amdhsa_kernarg_size 432
		.amdhsa_user_sgpr_count 2
		.amdhsa_user_sgpr_dispatch_ptr 0
		.amdhsa_user_sgpr_queue_ptr 0
		.amdhsa_user_sgpr_kernarg_segment_ptr 1
		.amdhsa_user_sgpr_dispatch_id 0
		.amdhsa_user_sgpr_kernarg_preload_length 0
		.amdhsa_user_sgpr_kernarg_preload_offset 0
		.amdhsa_user_sgpr_private_segment_size 0
		.amdhsa_uses_dynamic_stack 0
		.amdhsa_enable_private_segment 0
		.amdhsa_system_sgpr_workgroup_id_x 1
		.amdhsa_system_sgpr_workgroup_id_y 0
		.amdhsa_system_sgpr_workgroup_id_z 0
		.amdhsa_system_sgpr_workgroup_info 0
		.amdhsa_system_vgpr_workitem_id 2
		.amdhsa_next_free_vgpr 256
		.amdhsa_next_free_sgpr 102
		.amdhsa_accum_offset 256
		.amdhsa_reserve_vcc 1
		.amdhsa_float_round_mode_32 0
		.amdhsa_float_round_mode_16_64 0
		.amdhsa_float_denorm_mode_32 3
		.amdhsa_float_denorm_mode_16_64 3
		.amdhsa_dx10_clamp 1
		.amdhsa_ieee_mode 1
		.amdhsa_fp16_overflow 0
		.amdhsa_tg_split 0
		.amdhsa_exception_fp_ieee_invalid_op 0
		.amdhsa_exception_fp_denorm_src 0
		.amdhsa_exception_fp_ieee_div_zero 0
		.amdhsa_exception_fp_ieee_overflow 0
		.amdhsa_exception_fp_ieee_underflow 0
		.amdhsa_exception_fp_ieee_inexact 0
		.amdhsa_exception_int_div_zero 0
	.end_amdhsa_kernel

amdhsa.kernels:
  - .agpr_count:     0
    .args:
      - .offset:         0
        .size:           176
        .value_kind:     by_value
      - .offset:         176
        .size:           4
        .value_kind:     hidden_block_count_x
      - .offset:         180
        .size:           4
        .value_kind:     hidden_block_count_y
      - .offset:         184
        .size:           4
        .value_kind:     hidden_block_count_z
      - .offset:         188
        .size:           2
        .value_kind:     hidden_group_size_x
      - .offset:         190
        .size:           2
        .value_kind:     hidden_group_size_y
      - .offset:         192
        .size:           2
        .value_kind:     hidden_group_size_z
      - .offset:         194
        .size:           2
        .value_kind:     hidden_remainder_x
      - .offset:         196
        .size:           2
        .value_kind:     hidden_remainder_y
      - .offset:         198
        .size:           2
        .value_kind:     hidden_remainder_z
      - .offset:         216
        .size:           8
        .value_kind:     hidden_global_offset_x
      - .offset:         224
        .size:           8
        .value_kind:     hidden_global_offset_y
      - .offset:         232
        .size:           8
        .value_kind:     hidden_global_offset_z
      - .offset:         240
        .size:           2
        .value_kind:     hidden_grid_dims
      - .offset:         264
        .size:           8
        .value_kind:     hidden_multigrid_sync_arg
      - .offset:         296
        .size:           4
        .value_kind:     hidden_dynamic_lds_size
    .group_segment_fixed_size: 0
    .kernarg_segment_align: 8
    .kernarg_segment_size: 432
    .language:       OpenCL C
    .language_version:
      - 2
      - 0
    .max_flat_workgroup_size: 512
    .name:           _Z8fwd_mega4Args
    .private_segment_fixed_size: 0
    .sgpr_count:     108
    .sgpr_spill_count: 12
    .symbol:         _Z8fwd_mega4Args.kd
    .uniform_work_group_size: 1
    .uses_dynamic_stack: false
    .vgpr_count:     256
    .vgpr_spill_count: 0
    .wavefront_size: 64
